# LDS fragment reads hoisted/retargeted to free VGPR quads with recounted lgkmcnt waits in ret_out (QK, PV, inter-chunk) and NA attention; on top of scan read hoist, widened ret_out stores, ret_out L2 p
# speedup vs baseline: 1.0077x; 1.0077x over previous
; template <bool UPFRONT, class KP, class VP, class MOD>
; __device__ __forceinline__ void attn16(const bf16x8 (&qf)[2], KP kptr, VP vptr, MOD mod, bf16_t* outp  , int fr, int fq) {
;     bf16x8 kf[16][2];
; #pragma unroll
;     for (int t = 0; t < 16; ++t) if (UPFRONT) { const int key = 32 * (t >> 1) + 8 * (fr >> 2) + 4 * (t & 1) + (fr & 3); kf[t][0] = kptr(key, 0); kf[t][1] = kptr(key, 1); }
;     f32x4 st[16];
;     float mx = -3.0e38f;
; #pragma unroll
;     for (int t = 0; t < 16; ++t) {
;         f32x4 acc = (f32x4){0.f, 0.f, 0.f, 0.f};
;         if (!UPFRONT) { const int key = 32 * (t >> 1) + 8 * (fr >> 2) + 4 * (t & 1) + (fr & 3); kf[t][0] = kptr(key, 0); kf[t][1] = kptr(key, 1); }
;         acc = __builtin_amdgcn_mfma_f32_16x16x32_bf16(kf[t][0], qf[0], acc, 0, 0, 0);
;         acc = __builtin_amdgcn_mfma_f32_16x16x32_bf16(kf[t][1], qf[1], acc, 0, 0, 0);
; #pragma unroll
;         for (int r = 0; r < 4; ++r) { const float v = mod(acc[r], t >> 1, t & 1, r); acc[r] = v; mx = fmaxf(mx, v); }
;         st[t] = acc;
;     }
; __device__ __forceinline__ void na_phase(const bf16_t* proj, const bf16_t* vT, const float* rpb, bf16_t* mix, unsigned char* lds, int tid, int bx) {
;     ...
;             int fqx = fq; asm volatile("" : "+v"(fqx));
;             int sl[8];
; #pragma unroll
;             for (int q = 0; q < 8; ++q) sl[q] = (rs + q) % 9;
;             bf16x8 qf[2]; qf[0] = qfe[0]; qf[1] = qfe[1];
;             const float* rp = lrp + (rs - r + 7) * 31;
;             const int gk = ((fr >> 1) & 1) | ((((kstart >> 3) + (fr >> 2)) & 3) << 1);
;             const unsigned char* kimg = lds + (kstart + 8 * (fr >> 2) + (fr & 3)) * 128;
;             const unsigned char* vimg = lds + NA_VOFF + ((kstart >> 3) + fqx) * 16;
;             attn16<false>(qf,
;                    [&](int key, int ks) { return *(const bf16x8*)(kimg + sl[key >> 5] * 8192 + ((key >> 2) & 1) * 512 + (((4 * ks + fqx) ^ gk) << 4)); },
;                    [&](int d, int s) { return *(const bf16x8*)(vimg + d * NA_VP + sl[s] * 128); },
;                    [&](float v, int s, int pp, int rr) { const int ix = pp * 4 + rr; const unsigned dc = (ix & 1) ? (dcp[ix >> 1] >> 16) : (dcp[ix >> 1] & 0xffffu); return v * 0.125f + rp[s * 31 + dc]; },
.LBB0_168:
	s_cmp_gt_i32 s1, 3
	s_cselect_b32 s0, s6, 0
	s_mul_i32 s1, s0, 57
	s_lshr_b32 s6, s1, 9
	s_mul_i32 s6, s6, 9
	s_sub_i32 s6, s0, s6
	s_and_b32 s34, s6, 0xff
	s_add_i32 s6, s1, 57
	s_bfe_u32 s6, s6, 0x40009
	s_mul_i32 s6, s6, 9
	s_sub_i32 s6, s0, s6
	s_add_i32 s6, s6, 1
	s_and_b32 s31, s6, 0xff
	s_add_i32 s6, s1, 0x72
	s_bfe_u32 s6, s6, 0x40009
	s_mul_i32 s6, s6, 9
	s_sub_i32 s6, s0, s6
	s_add_i32 s6, s6, 2
	s_and_b32 s30, s6, 0xff
	s_add_i32 s6, s1, 0xab
	s_bfe_u32 s6, s6, 0x40009
	s_mul_i32 s6, s6, 9
	v_mov_b32_e32 v102, v184
	s_sub_i32 s6, s0, s6
	v_ashrrev_i32_e32 v99, 31, v98
	s_waitcnt lgkmcnt(0)
	s_barrier
	s_add_i32 s6, s6, 3
	v_add_u32_e32 v100, v102, v187
	s_and_b32 s29, s6, 0xff
	s_add_i32 s6, s1, 0xe4
	v_lshl_add_u32 v210, v100, 4, s73
	v_lshlrev_b64 v[100:101], 11, v[98:99]
	v_xor_b32_e32 v99, v102, v188
	s_bfe_u32 s6, s6, 0x40009
	v_lshlrev_b32_e32 v213, 4, v99
	v_add_u32_e32 v99, 4, v102
	s_mul_i32 s6, s6, 9
	v_xor_b32_e32 v99, v99, v188
	s_sub_i32 s6, s0, s6
	v_lshlrev_b32_e32 v211, 4, v99
	v_lshl_add_u32 v99, s34, 13, v189
	s_add_i32 s6, s6, 4
	v_add_u32_e32 v114, v99, v213
	ds_read_b128 v[236:239], v114
	s_and_b32 s28, s6, 0xff
	s_add_i32 s6, s1, 0x11d
	s_bfe_u32 s6, s6, 0x40009
	s_mul_i32 s6, s6, 9
	s_sub_i32 s6, s0, s6
	v_add_u32_e32 v115, v99, v211
	ds_read_b128 v[240:243], v115
	s_add_i32 s6, s6, 5
	s_and_b32 s15, s6, 0xff
	s_add_i32 s6, s1, 0x156
	s_addk_i32 s1, 0x18f
	s_bfe_u32 s6, s6, 0x40009
	s_bfe_u32 s1, s1, 0x40009
	s_mul_i32 s6, s6, 9
	s_mul_i32 s1, s1, 9
	s_sub_i32 s6, s0, s6
	s_sub_i32 s1, s0, s1
	s_add_i32 s0, s0, s52
	s_mulk_i32 s0, 0x7c
	s_waitcnt vmcnt(1)
	s_waitcnt lgkmcnt(1)
	v_mfma_f32_16x16x32_bf16 v[102:105], v[236:239], v[76:79], 0
	ds_read_b128 v[236:239], v114 offset:512
	s_add_i32 s0, s0, 0
	s_add_i32 s0, s0, 0x24800
	v_lshl_add_u32 v130, v191, 2, s0
	v_lshl_add_u32 v131, v192, 2, s0
	s_waitcnt vmcnt(0)
	s_waitcnt lgkmcnt(1)
	v_mfma_f32_16x16x32_bf16 v[110:113], v[240:243], v[72:75], v[102:105]
	ds_read_b128 v[240:243], v115 offset:512
	ds_read2_b32 v[108:109], v130 offset0:217 offset1:248
	ds_read2_b32 v[106:107], v131 offset0:217 offset1:248
	v_lshl_add_u32 v132, v193, 2, s0
	v_lshl_add_u32 v133, v194, 2, s0
	ds_read2_b32 v[104:105], v132 offset0:217 offset1:248
	ds_read2_b32 v[102:103], v133 offset0:217 offset1:248
	s_nop 0
	s_waitcnt lgkmcnt(3)
	v_fmamk_f32 v108, v110, 0x3e000000, v108
	s_waitcnt lgkmcnt(2)
	v_fmamk_f32 v106, v111, 0x3e000000, v106
	v_max3_f32 v110, v108, s62, v106
	s_waitcnt lgkmcnt(1)
	v_fmamk_f32 v104, v112, 0x3e000000, v104
	s_waitcnt lgkmcnt(0)
	v_fmamk_f32 v99, v113, 0x3e000000, v102
	v_max3_f32 v102, v110, v104, v99
	v_mfma_f32_16x16x32_bf16 v[110:113], v[236:239], v[76:79], 0
	v_lshl_add_u32 v136, v195, 2, s0
	v_lshl_add_u32 v137, v196, 2, s0
	v_lshl_add_u32 v138, v197, 2, s0
	v_mfma_f32_16x16x32_bf16 v[116:119], v[240:243], v[72:75], v[110:113]
	ds_read2_b32 v[114:115], v136 offset0:217 offset1:248
	v_lshl_add_u32 v139, v198, 2, s0
	v_add_u32_e32 v150, 0x400, v130
	ds_read2_b32 v[112:113], v137 offset0:217 offset1:248
	ds_read2_b32 v[110:111], v139 offset0:217 offset1:248
	s_nop 1
	s_waitcnt lgkmcnt(2)
	v_fmamk_f32 v212, v116, 0x3e000000, v114
	v_add_u32_e32 v151, 0x400, v131
	v_add_u32_e32 v152, 0x400, v132
	s_waitcnt lgkmcnt(1)
	v_fmamk_f32 v112, v117, 0x3e000000, v112
	ds_read2_b32 v[116:117], v138 offset0:217 offset1:248
	v_max3_f32 v120, v102, v212, v112
	s_waitcnt lgkmcnt(1)
	v_fmamk_f32 v102, v119, 0x3e000000, v110
	v_add_u32_e32 v164, 0x400, v133
	v_add_u32_e32 v165, 0x400, v136
	s_waitcnt lgkmcnt(0)
	v_fmamk_f32 v114, v118, 0x3e000000, v116
	v_lshl_add_u32 v116, s31, 13, v189
	v_add_u32_e32 v126, v116, v213
	ds_read_b128 v[236:239], v126
	v_max3_f32 v110, v120, v114, v102
	v_add_u32_e32 v116, v116, v211
	ds_read_b128 v[240:243], v116
	s_waitcnt lgkmcnt(1)
	v_mfma_f32_16x16x32_bf16 v[118:121], v[236:239], v[76:79], 0
	ds_read_b128 v[236:239], v126 offset:512
	v_add_u32_e32 v166, 0x400, v137
	v_add_u32_e32 v167, 0x400, v138
	v_add_u32_e32 v214, 0x400, v139
	s_waitcnt lgkmcnt(1)
	v_mfma_f32_16x16x32_bf16 v[118:121], v[240:243], v[72:75], v[118:121]
	ds_read_b128 v[240:243], v116 offset:512
	s_add_i32 s6, s6, 6
	s_and_b32 s14, s6, 0xff
	s_add_i32 s1, s1, 7
	s_and_b32 s6, s1, 0xff
	s_nop 3
	v_fmac_f32_e32 v109, 0x3e000000, v118
	v_fmac_f32_e32 v107, 0x3e000000, v119
	v_fmac_f32_e32 v105, 0x3e000000, v120
	v_fmac_f32_e32 v103, 0x3e000000, v121
	s_waitcnt lgkmcnt(1)
	v_mfma_f32_16x16x32_bf16 v[118:121], v[236:239], v[76:79], 0
	v_lshl_add_u32 v116, s30, 13, v189
	v_add_u32_e32 v134, v116, v213
	v_add_u32_e32 v135, v116, v211
	ds_read_b128 v[236:239], v135
	s_waitcnt lgkmcnt(1)
	v_mfma_f32_16x16x32_bf16 v[118:121], v[240:243], v[72:75], v[118:121]
	ds_read_b128 v[240:243], v134
	v_max3_f32 v110, v110, v109, v107
	v_max3_f32 v110, v110, v105, v103
	s_nop 4
	v_fmac_f32_e32 v115, 0x3e000000, v118
	v_fmac_f32_e32 v113, 0x3e000000, v119
	v_fmac_f32_e32 v117, 0x3e000000, v120
	v_fmac_f32_e32 v111, 0x3e000000, v121
	s_waitcnt lgkmcnt(0)
	v_mfma_f32_16x16x32_bf16 v[118:121], v[240:243], v[76:79], 0
	ds_read_b128 v[240:243], v134 offset:512
	v_max3_f32 v110, v110, v115, v113
	v_max3_f32 v110, v110, v117, v111
	v_mfma_f32_16x16x32_bf16 v[126:129], v[236:239], v[72:75], v[118:121]
	ds_read_b128 v[236:239], v135 offset:512
	ds_read2_b32 v[124:125], v150 offset0:23 offset1:54
	ds_read2_b32 v[122:123], v151 offset0:23 offset1:54
	s_nop 2
	ds_read2_b32 v[120:121], v152 offset0:23 offset1:54
	ds_read2_b32 v[118:119], v164 offset0:23 offset1:54
	s_waitcnt lgkmcnt(3)
	v_fmamk_f32 v124, v126, 0x3e000000, v124
	s_waitcnt lgkmcnt(2)
; template <bool UPFRONT, class KP, class VP, class MOD>
; __device__ __forceinline__ void attn16(const bf16x8 (&qf)[2], KP kptr, VP vptr, MOD mod, bf16_t* outp  , int fr, int fq) {
;     ...
;     for (int t = 0; t < 16; ++t) {
;         f32x4 acc = (f32x4){0.f, 0.f, 0.f, 0.f};
;         if (!UPFRONT) { const int key = 32 * (t >> 1) + 8 * (fr >> 2) + 4 * (t & 1) + (fr & 3); kf[t][0] = kptr(key, 0); kf[t][1] = kptr(key, 1); }
;         acc = __builtin_amdgcn_mfma_f32_16x16x32_bf16(kf[t][0], qf[0], acc, 0, 0, 0);
;         acc = __builtin_amdgcn_mfma_f32_16x16x32_bf16(kf[t][1], qf[1], acc, 0, 0, 0);
; #pragma unroll
;         for (int r = 0; r < 4; ++r) { const float v = mod(acc[r], t >> 1, t & 1, r); acc[r] = v; mx = fmaxf(mx, v); }
;         st[t] = acc;
;     }
; __device__ __forceinline__ void na_phase(const bf16_t* proj, const bf16_t* vT, const float* rpb, bf16_t* mix, unsigned char* lds, int tid, int bx) {
;     ...
;                    [&](float v, int s, int pp, int rr) { const int ix = pp * 4 + rr; const unsigned dc = (ix & 1) ? (dcp[ix >> 1] >> 16) : (dcp[ix >> 1] & 0xffffu); return v * 0.125f + rp[s * 31 + dc]; },
	v_fmamk_f32 v122, v127, 0x3e000000, v122
	v_max3_f32 v126, v110, v124, v122
	s_waitcnt lgkmcnt(1)
	v_fmamk_f32 v116, v128, 0x3e000000, v120
	s_waitcnt lgkmcnt(0)
	v_fmamk_f32 v110, v129, 0x3e000000, v118
	v_max3_f32 v118, v126, v116, v110
	v_mfma_f32_16x16x32_bf16 v[126:129], v[240:243], v[76:79], 0
	v_mfma_f32_16x16x32_bf16 v[132:135], v[236:239], v[72:75], v[126:129]
	ds_read2_b32 v[130:131], v165 offset0:23 offset1:54
	s_nop 4
	ds_read2_b32 v[128:129], v166 offset0:23 offset1:54
	ds_read2_b32 v[126:127], v214 offset0:23 offset1:54
	s_waitcnt lgkmcnt(2)
	v_fmamk_f32 v120, v132, 0x3e000000, v130
	s_waitcnt lgkmcnt(1)
	v_fmamk_f32 v128, v133, 0x3e000000, v128
	ds_read2_b32 v[132:133], v167 offset0:23 offset1:54
	v_max3_f32 v136, v118, v120, v128
	s_waitcnt lgkmcnt(1)
	v_fmamk_f32 v118, v135, 0x3e000000, v126
	s_waitcnt lgkmcnt(0)
	v_fmamk_f32 v130, v134, 0x3e000000, v132
	v_lshl_add_u32 v132, s29, 13, v189
	v_add_u32_e32 v142, v132, v213
	ds_read_b128 v[240:243], v142
	v_max3_f32 v126, v136, v130, v118
	v_add_u32_e32 v132, v132, v211
	ds_read_b128 v[236:239], v132
	s_waitcnt lgkmcnt(1)
	v_mfma_f32_16x16x32_bf16 v[134:137], v[240:243], v[76:79], 0
	ds_read_b128 v[240:243], v142 offset:512
	s_waitcnt lgkmcnt(1)
	v_mfma_f32_16x16x32_bf16 v[134:137], v[236:239], v[72:75], v[134:137]
	ds_read_b128 v[236:239], v132 offset:512
	s_nop 7
	v_fmac_f32_e32 v125, 0x3e000000, v134
	v_fmac_f32_e32 v123, 0x3e000000, v135
	v_fmac_f32_e32 v121, 0x3e000000, v136
	v_fmac_f32_e32 v119, 0x3e000000, v137
	s_waitcnt lgkmcnt(1)
	v_mfma_f32_16x16x32_bf16 v[134:137], v[240:243], v[76:79], 0
	v_lshl_add_u32 v132, s28, 13, v189
	v_add_u32_e32 v146, v132, v213
	v_add_u32_e32 v147, v132, v211
	ds_read_b128 v[240:243], v147
	s_waitcnt lgkmcnt(1)
	v_mfma_f32_16x16x32_bf16 v[134:137], v[236:239], v[72:75], v[134:137]
	ds_read_b128 v[236:239], v146
	v_max3_f32 v126, v126, v125, v123
	v_max3_f32 v126, v126, v121, v119
	s_nop 4
	v_fmac_f32_e32 v131, 0x3e000000, v134
	v_fmac_f32_e32 v129, 0x3e000000, v135
	v_fmac_f32_e32 v133, 0x3e000000, v136
	v_fmac_f32_e32 v127, 0x3e000000, v137
	s_waitcnt lgkmcnt(0)
	v_mfma_f32_16x16x32_bf16 v[134:137], v[236:239], v[76:79], 0
	ds_read_b128 v[236:239], v146 offset:512
	v_max3_f32 v126, v126, v131, v129
	v_max3_f32 v126, v126, v133, v127
	v_mfma_f32_16x16x32_bf16 v[142:145], v[240:243], v[72:75], v[134:137]
	ds_read_b128 v[240:243], v147 offset:512
	ds_read2_b32 v[140:141], v150 offset0:85 offset1:116
	ds_read2_b32 v[138:139], v151 offset0:85 offset1:116
	s_nop 2
	ds_read2_b32 v[136:137], v152 offset0:85 offset1:116
	ds_read2_b32 v[134:135], v164 offset0:85 offset1:116
	s_waitcnt lgkmcnt(3)
	v_fmamk_f32 v140, v142, 0x3e000000, v140
	s_waitcnt lgkmcnt(2)
	v_fmamk_f32 v138, v143, 0x3e000000, v138
	v_max3_f32 v142, v126, v140, v138
	s_waitcnt lgkmcnt(1)
	v_fmamk_f32 v132, v144, 0x3e000000, v136
	s_waitcnt lgkmcnt(0)
	v_fmamk_f32 v126, v145, 0x3e000000, v134
	v_max3_f32 v134, v142, v132, v126
	v_mfma_f32_16x16x32_bf16 v[142:145], v[236:239], v[76:79], 0
	v_mfma_f32_16x16x32_bf16 v[160:163], v[240:243], v[72:75], v[142:145]
	ds_read2_b32 v[148:149], v165 offset0:85 offset1:116
	ds_read2_b32 v[146:147], v166 offset0:85 offset1:116
	s_nop 3
	ds_read2_b32 v[144:145], v167 offset0:85 offset1:116
	ds_read2_b32 v[142:143], v214 offset0:85 offset1:116
	s_waitcnt lgkmcnt(3)
	v_fmamk_f32 v148, v160, 0x3e000000, v148
	s_waitcnt lgkmcnt(2)
	v_fmamk_f32 v146, v161, 0x3e000000, v146
	v_max3_f32 v153, v134, v148, v146
	s_waitcnt lgkmcnt(1)
	v_fmamk_f32 v136, v162, 0x3e000000, v144
	s_waitcnt lgkmcnt(0)
	v_fmamk_f32 v134, v163, 0x3e000000, v142
	v_lshl_add_u32 v144, s15, 13, v189
	v_max3_f32 v142, v153, v136, v134
	v_add_u32_e32 v153, v144, v213
	ds_read_b128 v[236:239], v153
	v_add_u32_e32 v144, v144, v211
	ds_read_b128 v[240:243], v144
	s_waitcnt lgkmcnt(1)
	v_mfma_f32_16x16x32_bf16 v[160:163], v[236:239], v[76:79], 0
	ds_read_b128 v[236:239], v153 offset:512
	s_waitcnt lgkmcnt(1)
	v_mfma_f32_16x16x32_bf16 v[160:163], v[240:243], v[72:75], v[160:163]
	ds_read_b128 v[240:243], v144 offset:512
	s_nop 7
	v_fmac_f32_e32 v141, 0x3e000000, v160
	v_fmac_f32_e32 v139, 0x3e000000, v161
	v_fmac_f32_e32 v137, 0x3e000000, v162
	v_fmac_f32_e32 v135, 0x3e000000, v163
	s_waitcnt lgkmcnt(1)
	v_mfma_f32_16x16x32_bf16 v[160:163], v[236:239], v[76:79], 0
	v_lshl_add_u32 v144, s14, 13, v189
	v_add_u32_e32 v215, v144, v213
	v_add_u32_e32 v216, v144, v211
	ds_read_b128 v[236:239], v216
	s_waitcnt lgkmcnt(1)
	v_mfma_f32_16x16x32_bf16 v[160:163], v[240:243], v[72:75], v[160:163]
	ds_read_b128 v[240:243], v215
	ds_read2_b32 v[152:153], v152 offset0:147 offset1:178
	v_max3_f32 v142, v142, v141, v139
	v_max3_f32 v142, v142, v137, v135
	s_nop 3
	v_fmac_f32_e32 v149, 0x3e000000, v160
	v_fmac_f32_e32 v147, 0x3e000000, v161
	v_fmac_f32_e32 v145, 0x3e000000, v162
	v_fmac_f32_e32 v143, 0x3e000000, v163
	s_waitcnt lgkmcnt(1)
	v_mfma_f32_16x16x32_bf16 v[160:163], v[240:243], v[76:79], 0
	ds_read_b128 v[240:243], v215 offset:512
	v_max3_f32 v142, v142, v149, v147
	v_max3_f32 v142, v142, v145, v143
	v_mfma_f32_16x16x32_bf16 v[168:171], v[236:239], v[72:75], v[160:163]
	ds_read_b128 v[236:239], v216 offset:512
	s_nop 4
	ds_read2_b32 v[162:163], v150 offset0:147 offset1:178
	ds_read2_b32 v[160:161], v151 offset0:147 offset1:178
	ds_read2_b32 v[150:151], v164 offset0:147 offset1:178
	s_waitcnt lgkmcnt(5)
	v_fmamk_f32 v144, v170, 0x3e000000, v152
	v_lshl_add_u32 v152, s6, 13, v189
	s_waitcnt lgkmcnt(2)
	v_fmamk_f32 v162, v168, 0x3e000000, v162
	s_waitcnt lgkmcnt(1)
	v_fmamk_f32 v160, v169, 0x3e000000, v160
	v_max3_f32 v168, v142, v162, v160
	s_waitcnt lgkmcnt(0)
; template <bool UPFRONT, class KP, class VP, class MOD>
; __device__ __forceinline__ void attn16(const bf16x8 (&qf)[2], KP kptr, VP vptr, MOD mod, bf16_t* outp  , int fr, int fq) {
;     ...
;     for (int t = 0; t < 16; ++t) {
;         f32x4 acc = (f32x4){0.f, 0.f, 0.f, 0.f};
;         if (!UPFRONT) { const int key = 32 * (t >> 1) + 8 * (fr >> 2) + 4 * (t & 1) + (fr & 3); kf[t][0] = kptr(key, 0); kf[t][1] = kptr(key, 1); }
;         acc = __builtin_amdgcn_mfma_f32_16x16x32_bf16(kf[t][0], qf[0], acc, 0, 0, 0);
;         acc = __builtin_amdgcn_mfma_f32_16x16x32_bf16(kf[t][1], qf[1], acc, 0, 0, 0);
; #pragma unroll
;         for (int r = 0; r < 4; ++r) { const float v = mod(acc[r], t >> 1, t & 1, r); acc[r] = v; mx = fmaxf(mx, v); }
;         st[t] = acc;
;     }
;     __builtin_amdgcn_sched_barrier(0);
;     bf16x8 vf[8][4];
; #pragma unroll
;     for (int s = 0; s < 8; ++s)
; #pragma unroll
;         for (int dt = 0; dt < 4; ++dt) if (UPFRONT) vf[s][dt] = vptr(16 * dt + fr, s);
;     mx = fmaxf(mx, __shfl_xor(mx, 16)); mx = fmaxf(mx, __shfl_xor(mx, 32));
;     float sum = 0.f;
; #pragma unroll
;     for (int t = 0; t < 16; ++t)
; #pragma unroll
;         for (int r = 0; r < 4; ++r) { const float e = __expf(st[t][r] - mx); st[t][r] = e; sum += e; }
	v_fmamk_f32 v142, v171, 0x3e000000, v150
	v_max3_f32 v150, v168, v144, v142
	v_mfma_f32_16x16x32_bf16 v[168:171], v[240:243], v[76:79], 0
	ds_read2_b32 v[164:165], v165 offset0:147 offset1:178
	v_mfma_f32_16x16x32_bf16 v[216:219], v[236:239], v[72:75], v[168:171]
	s_nop 4
	ds_read2_b32 v[170:171], v166 offset0:147 offset1:178
	ds_read2_b32 v[168:169], v167 offset0:147 offset1:178
	s_waitcnt lgkmcnt(2)
	v_fmamk_f32 v220, v216, 0x3e000000, v164
	v_add_u32_e32 v164, v152, v213
	ds_read_b128 v[240:243], v164
	ds_read2_b32 v[166:167], v214 offset0:147 offset1:178
	s_waitcnt lgkmcnt(3)
	v_fmamk_f32 v224, v217, 0x3e000000, v170
	v_add_u32_e32 v152, v152, v211
	ds_read_b128 v[236:239], v152
	s_waitcnt lgkmcnt(2)
	v_mfma_f32_16x16x32_bf16 v[214:217], v[240:243], v[76:79], 0
	ds_read_b128 v[240:243], v164 offset:512
	v_max3_f32 v150, v150, v220, v224
	v_fmamk_f32 v223, v218, 0x3e000000, v168
	s_waitcnt lgkmcnt(2)
	v_fmamk_f32 v221, v219, 0x3e000000, v166
	s_waitcnt lgkmcnt(1)
	v_mfma_f32_16x16x32_bf16 v[214:217], v[236:239], v[72:75], v[214:217]
	ds_read_b128 v[236:239], v152 offset:512
	v_max3_f32 v150, v150, v223, v221
	s_nop 6
	v_fmac_f32_e32 v163, 0x3e000000, v214
	v_fmac_f32_e32 v161, 0x3e000000, v215
	v_fmac_f32_e32 v153, 0x3e000000, v216
	v_fmac_f32_e32 v151, 0x3e000000, v217
	s_waitcnt lgkmcnt(1)
	v_mfma_f32_16x16x32_bf16 v[76:79], v[240:243], v[76:79], 0
	v_max3_f32 v150, v150, v163, v161
	v_max3_f32 v150, v150, v153, v151
	s_waitcnt lgkmcnt(0)
	v_mfma_f32_16x16x32_bf16 v[72:75], v[236:239], v[72:75], v[76:79]
	s_nop 7
	v_fmac_f32_e32 v165, 0x3e000000, v72
	v_fmac_f32_e32 v171, 0x3e000000, v73
	v_fmac_f32_e32 v169, 0x3e000000, v74
	v_fmac_f32_e32 v167, 0x3e000000, v75
	v_max3_f32 v72, v150, v165, v171
	v_max3_f32 v72, v72, v169, v167
	ds_bpermute_b32 v73, v199, v72
	s_lshl_b32 s0, s34, 7
	s_waitcnt lgkmcnt(0)
	v_max_f32_e32 v73, v73, v73
	v_max_f32_e32 v72, v72, v73
	ds_bpermute_b32 v73, v200, v72
	s_waitcnt lgkmcnt(0)
	v_max_f32_e32 v73, v73, v73
	v_max_f32_e32 v73, v72, v73
	v_sub_f32_e32 v77, v99, v73
	v_mul_f32_e32 v77, 0x3fb8aa3b, v77
	v_exp_f32_e32 v230, v77
	v_sub_f32_e32 v77, v212, v73
	v_mul_f32_e32 v77, 0x3fb8aa3b, v77
	v_exp_f32_e32 v231, v77
	v_sub_f32_e32 v77, v112, v73
	v_mul_f32_e32 v77, 0x3fb8aa3b, v77
	v_exp_f32_e32 v232, v77
	v_sub_f32_e32 v77, v114, v73
	v_mul_f32_e32 v77, 0x3fb8aa3b, v77
	v_exp_f32_e32 v233, v77
	v_sub_f32_e32 v77, v102, v73
	v_mul_f32_e32 v77, 0x3fb8aa3b, v77
	v_exp_f32_e32 v234, v77
	v_sub_f32_e32 v77, v109, v73
	v_mul_f32_e32 v77, 0x3fb8aa3b, v77
	v_exp_f32_e32 v212, v77
	v_sub_f32_e32 v77, v107, v73
	v_mul_f32_e32 v77, 0x3fb8aa3b, v77
	v_exp_f32_e32 v214, v77
	v_sub_f32_e32 v77, v105, v73
	v_mul_f32_e32 v77, 0x3fb8aa3b, v77
	v_exp_f32_e32 v217, v77
	v_sub_f32_e32 v77, v103, v73
	v_mul_f32_e32 v77, 0x3fb8aa3b, v77
	v_exp_f32_e32 v222, v77
	v_sub_f32_e32 v77, v115, v73
	v_mul_f32_e32 v77, 0x3fb8aa3b, v77
	v_exp_f32_e32 v225, v77
	v_sub_f32_e32 v77, v113, v73
	v_mul_f32_e32 v77, 0x3fb8aa3b, v77
	v_exp_f32_e32 v227, v77
	v_sub_f32_e32 v77, v117, v73
	v_mul_f32_e32 v77, 0x3fb8aa3b, v77
	v_exp_f32_e32 v228, v77
	v_sub_f32_e32 v77, v111, v73
	v_mul_f32_e32 v77, 0x3fb8aa3b, v77
	v_exp_f32_e32 v229, v77
	v_sub_f32_e32 v77, v124, v73
	v_mul_f32_e32 v77, 0x3fb8aa3b, v77
	v_exp_f32_e32 v150, v77
	v_sub_f32_e32 v77, v122, v73
	v_mul_f32_e32 v77, 0x3fb8aa3b, v77
	v_exp_f32_e32 v164, v77
	v_sub_f32_e32 v77, v116, v73
	v_mul_f32_e32 v77, 0x3fb8aa3b, v77
	v_exp_f32_e32 v168, v77
	v_sub_f32_e32 v77, v110, v73
	v_mul_f32_e32 v77, 0x3fb8aa3b, v77
	v_exp_f32_e32 v213, v77
	v_sub_f32_e32 v77, v120, v73
	v_mul_f32_e32 v77, 0x3fb8aa3b, v77
	v_exp_f32_e32 v215, v77
	v_sub_f32_e32 v77, v128, v73
	v_mul_f32_e32 v77, 0x3fb8aa3b, v77
	v_exp_f32_e32 v218, v77
	v_sub_f32_e32 v77, v130, v73
	v_mul_f32_e32 v77, 0x3fb8aa3b, v77
	v_exp_f32_e32 v219, v77
	v_sub_f32_e32 v77, v118, v73
	v_mul_f32_e32 v77, 0x3fb8aa3b, v77
	v_exp_f32_e32 v226, v77
	v_sub_f32_e32 v77, v125, v73
	v_mul_f32_e32 v77, 0x3fb8aa3b, v77
	v_exp_f32_e32 v125, v77
	v_sub_f32_e32 v77, v123, v73
	v_mul_f32_e32 v77, 0x3fb8aa3b, v77
	v_exp_f32_e32 v128, v77
	v_sub_f32_e32 v77, v121, v73
	v_mul_f32_e32 v77, 0x3fb8aa3b, v77
	v_exp_f32_e32 v130, v77
	v_sub_f32_e32 v77, v119, v73
	v_mul_f32_e32 v77, 0x3fb8aa3b, v77
	v_exp_f32_e32 v152, v77
	v_sub_f32_e32 v77, v131, v73
	v_sub_f32_e32 v72, v108, v73
	v_mul_f32_e32 v77, 0x3fb8aa3b, v77
	v_mul_f32_e32 v72, 0x3fb8aa3b, v72
	v_sub_f32_e32 v74, v106, v73
	v_exp_f32_e32 v166, v77
	v_sub_f32_e32 v77, v129, v73
	v_exp_f32_e32 v72, v72
	v_mul_f32_e32 v74, 0x3fb8aa3b, v74
	v_mul_f32_e32 v77, 0x3fb8aa3b, v77
	v_exp_f32_e32 v74, v74
	v_exp_f32_e32 v170, v77
	v_sub_f32_e32 v77, v133, v73
	v_mul_f32_e32 v77, 0x3fb8aa3b, v77
	v_exp_f32_e32 v211, v77
	v_sub_f32_e32 v77, v127, v73
	v_add_f32_e32 v75, 0, v72
	v_mul_f32_e32 v77, 0x3fb8aa3b, v77
	v_add_f32_e32 v76, v74, v75
	v_sub_f32_e32 v75, v104, v73
	v_exp_f32_e32 v216, v77
	v_sub_f32_e32 v77, v140, v73
	v_mul_f32_e32 v75, 0x3fb8aa3b, v75
	v_mul_f32_e32 v77, 0x3fb8aa3b, v77
	v_exp_f32_e32 v75, v75
	v_exp_f32_e32 v118, v77
	v_sub_f32_e32 v77, v138, v73
	v_mul_f32_e32 v77, 0x3fb8aa3b, v77
	v_exp_f32_e32 v120, v77
	v_sub_f32_e32 v77, v132, v73
	v_mul_f32_e32 v77, 0x3fb8aa3b, v77
	v_add_f32_e32 v76, v75, v76
	v_exp_f32_e32 v122, v77
	v_sub_f32_e32 v77, v126, v73
	v_add_f32_e32 v76, v230, v76
	v_mul_f32_e32 v77, 0x3fb8aa3b, v77
	v_add_f32_e32 v76, v231, v76
	v_exp_f32_e32 v126, v77
	v_sub_f32_e32 v77, v148, v73
	v_add_f32_e32 v76, v232, v76
	v_mul_f32_e32 v77, 0x3fb8aa3b, v77
	v_add_f32_e32 v76, v233, v76
	v_exp_f32_e32 v127, v77
	v_sub_f32_e32 v77, v146, v73
	v_add_f32_e32 v76, v234, v76
; template <bool UPFRONT, class KP, class VP, class MOD>
; __device__ __forceinline__ void attn16(const bf16x8 (&qf)[2], KP kptr, VP vptr, MOD mod, bf16_t* outp  , int fr, int fq) {
;     ...
;     mx = fmaxf(mx, __shfl_xor(mx, 16)); mx = fmaxf(mx, __shfl_xor(mx, 32));
;     float sum = 0.f;
; #pragma unroll
;     for (int t = 0; t < 16; ++t)
; #pragma unroll
;         for (int r = 0; r < 4; ++r) { const float e = __expf(st[t][r] - mx); st[t][r] = e; sum += e; }
;     sum += __shfl_xor(sum, 16); sum += __shfl_xor(sum, 32);
;     f32x4 o[4];
; #pragma unroll
;     for (int dt = 0; dt < 4; ++dt) o[dt] = (f32x4){0.f, 0.f, 0.f, 0.f};
; #pragma unroll
;     for (int s = 0; s < 8; ++s) {
;         u32x4 pw; pw.x = cvt_pk_bf16(st[2 * s][0], st[2 * s][1]); pw.y = cvt_pk_bf16(st[2 * s][2], st[2 * s][3]);
;         pw.z = cvt_pk_bf16(st[2 * s + 1][0], st[2 * s + 1][1]); pw.w = cvt_pk_bf16(st[2 * s + 1][2], st[2 * s + 1][3]);
;         bf16x8 pf; __builtin_memcpy(&pf, &pw, 16);
; #pragma unroll
;         for (int dt = 0; dt < 4; ++dt) { if (!UPFRONT) vf[s][dt] = vptr(16 * dt + fr, s); o[dt] = __builtin_amdgcn_mfma_f32_16x16x32_bf16(vf[s][dt], pf, o[dt], 0, 0, 0); }
	v_mul_f32_e32 v77, 0x3fb8aa3b, v77
	v_add_f32_e32 v76, v212, v76
	v_exp_f32_e32 v131, v77
	v_sub_f32_e32 v77, v136, v73
	v_add_f32_e32 v76, v214, v76
	v_mul_f32_e32 v77, 0x3fb8aa3b, v77
	v_add_f32_e32 v76, v217, v76
	v_exp_f32_e32 v132, v77
	v_sub_f32_e32 v77, v134, v73
	v_add_f32_e32 v76, v222, v76
	v_mul_f32_e32 v77, 0x3fb8aa3b, v77
	v_add_f32_e32 v76, v225, v76
	v_exp_f32_e32 v133, v77
	v_sub_f32_e32 v77, v141, v73
	v_add_f32_e32 v76, v227, v76
	v_mul_f32_e32 v77, 0x3fb8aa3b, v77
	v_add_f32_e32 v76, v228, v76
	v_exp_f32_e32 v110, v77
	v_sub_f32_e32 v77, v139, v73
	v_add_f32_e32 v76, v229, v76
	v_mul_f32_e32 v77, 0x3fb8aa3b, v77
	v_add_f32_e32 v76, v150, v76
	v_exp_f32_e32 v113, v77
	v_sub_f32_e32 v77, v137, v73
	v_add_f32_e32 v76, v164, v76
	v_mul_f32_e32 v77, 0x3fb8aa3b, v77
	v_add_f32_e32 v76, v168, v76
	v_exp_f32_e32 v116, v77
	v_sub_f32_e32 v77, v135, v73
	v_add_f32_e32 v76, v213, v76
	v_mul_f32_e32 v77, 0x3fb8aa3b, v77
	v_add_f32_e32 v76, v215, v76
	v_exp_f32_e32 v119, v77
	v_sub_f32_e32 v77, v149, v73
	v_add_f32_e32 v76, v218, v76
	v_mul_f32_e32 v77, 0x3fb8aa3b, v77
	v_add_f32_e32 v76, v219, v76
	v_exp_f32_e32 v121, v77
	v_sub_f32_e32 v77, v147, v73
	v_add_f32_e32 v76, v226, v76
	v_mul_f32_e32 v77, 0x3fb8aa3b, v77
	v_add_f32_e32 v76, v125, v76
	v_exp_f32_e32 v123, v77
	v_sub_f32_e32 v77, v145, v73
	v_add_f32_e32 v76, v128, v76
	v_mul_f32_e32 v77, 0x3fb8aa3b, v77
	v_add_f32_e32 v76, v130, v76
	v_exp_f32_e32 v124, v77
	v_sub_f32_e32 v77, v143, v73
	v_add_f32_e32 v76, v152, v76
	v_mul_f32_e32 v77, 0x3fb8aa3b, v77
	v_add_f32_e32 v76, v166, v76
	v_exp_f32_e32 v129, v77
	v_sub_f32_e32 v77, v162, v73
	v_add_f32_e32 v76, v170, v76
	v_mul_f32_e32 v77, 0x3fb8aa3b, v77
	v_add_f32_e32 v76, v211, v76
	v_exp_f32_e32 v107, v77
	v_sub_f32_e32 v77, v160, v73
	v_add_f32_e32 v76, v216, v76
	v_mul_f32_e32 v77, 0x3fb8aa3b, v77
	v_add_f32_e32 v76, v118, v76
	v_exp_f32_e32 v108, v77
	v_sub_f32_e32 v77, v144, v73
	v_add_f32_e32 v76, v120, v76
	v_mul_f32_e32 v77, 0x3fb8aa3b, v77
	v_add_f32_e32 v76, v122, v76
	v_exp_f32_e32 v109, v77
	v_sub_f32_e32 v77, v142, v73
	v_add_f32_e32 v76, v126, v76
	v_mul_f32_e32 v77, 0x3fb8aa3b, v77
	v_add_f32_e32 v76, v127, v76
	v_exp_f32_e32 v111, v77
	v_sub_f32_e32 v77, v220, v73
	v_add_f32_e32 v76, v131, v76
	v_mul_f32_e32 v77, 0x3fb8aa3b, v77
	v_add_f32_e32 v76, v132, v76
	v_exp_f32_e32 v112, v77
	v_sub_f32_e32 v77, v224, v73
	v_add_f32_e32 v76, v133, v76
	v_mul_f32_e32 v77, 0x3fb8aa3b, v77
	v_add_f32_e32 v76, v110, v76
	v_exp_f32_e32 v114, v77
	v_sub_f32_e32 v77, v223, v73
	v_add_f32_e32 v76, v113, v76
	v_mul_f32_e32 v77, 0x3fb8aa3b, v77
	v_add_f32_e32 v76, v116, v76
	v_exp_f32_e32 v115, v77
	v_sub_f32_e32 v77, v221, v73
	v_add_f32_e32 v76, v119, v76
	v_mul_f32_e32 v77, 0x3fb8aa3b, v77
	v_add_f32_e32 v76, v121, v76
	v_exp_f32_e32 v117, v77
	v_sub_f32_e32 v77, v163, v73
	v_add_f32_e32 v76, v123, v76
	v_mul_f32_e32 v77, 0x3fb8aa3b, v77
	v_add_f32_e32 v76, v124, v76
	v_exp_f32_e32 v78, v77
	v_sub_f32_e32 v77, v161, v73
	v_add_f32_e32 v76, v129, v76
	v_mul_f32_e32 v77, 0x3fb8aa3b, v77
	v_add_f32_e32 v76, v107, v76
	v_exp_f32_e32 v79, v77
	v_sub_f32_e32 v77, v153, v73
	v_add_f32_e32 v76, v108, v76
	v_mul_f32_e32 v77, 0x3fb8aa3b, v77
	v_add_f32_e32 v76, v109, v76
	v_exp_f32_e32 v99, v77
	v_sub_f32_e32 v77, v151, v73
	v_add_f32_e32 v76, v111, v76
	v_mul_f32_e32 v77, 0x3fb8aa3b, v77
	v_add_f32_e32 v76, v112, v76
	v_exp_f32_e32 v102, v77
	v_sub_f32_e32 v77, v165, v73
	v_add_f32_e32 v76, v114, v76
	v_mul_f32_e32 v77, 0x3fb8aa3b, v77
	v_add_f32_e32 v76, v115, v76
	v_exp_f32_e32 v103, v77
	v_sub_f32_e32 v77, v171, v73
	v_add_f32_e32 v76, v117, v76
	v_mul_f32_e32 v77, 0x3fb8aa3b, v77
	v_add_f32_e32 v76, v78, v76
	v_exp_f32_e32 v104, v77
	v_sub_f32_e32 v77, v169, v73
	v_add_f32_e32 v76, v79, v76
	v_mul_f32_e32 v77, 0x3fb8aa3b, v77
	v_sub_f32_e32 v73, v167, v73
	v_add_f32_e32 v76, v99, v76
	v_exp_f32_e32 v105, v77
	v_mul_f32_e32 v73, 0x3fb8aa3b, v73
	v_add_f32_e32 v76, v102, v76
	v_exp_f32_e32 v106, v73
	v_add_f32_e32 v76, v103, v76
	v_add3_u32 v146, v210, s0, v190
	ds_read_b128 v[240:243], v146
	ds_read_b128 v[236:239], v146 offset:37888
	v_add_f32_e32 v76, v104, v76
	v_add_f32_e32 v76, v105, v76
	v_add_f32_e32 v73, v106, v76
	s_lshl_b32 s0, s31, 7
	ds_bpermute_b32 v76, v199, v73
	ds_read_b128 v[138:141], v146 offset:18944
	ds_read_b128 v[146:149], v146 offset:56832
	v_add3_u32 v151, v210, s0, v190
	ds_read_b128 v[160:163], v151
	s_waitcnt lgkmcnt(3)
	v_add_f32_e32 v76, v73, v76
	v_cvt_pk_bf16_f32 v72, v72, v74
	v_cvt_pk_bf16_f32 v73, v75, v230
	v_cvt_pk_bf16_f32 v74, v231, v232
	v_cvt_pk_bf16_f32 v75, v233, v234
	s_lshl_b32 s0, s30, 7
	v_cvt_pk_bf16_f32 v119, v116, v119
	v_mfma_f32_16x16x32_bf16 v[134:137], v[240:243], v[72:75], 0
	ds_read_b128 v[240:243], v151 offset:18944
	v_cvt_pk_bf16_f32 v108, v107, v108
	v_cvt_pk_bf16_f32 v109, v109, v111
	v_cvt_pk_bf16_f32 v111, v115, v117
	s_waitcnt lgkmcnt(3)
	v_mfma_f32_16x16x32_bf16 v[138:141], v[138:141], v[72:75], 0
	ds_bpermute_b32 v77, v200, v76
	s_waitcnt lgkmcnt(0)
	v_add_f32_e32 v76, v76, v77
	v_mfma_f32_16x16x32_bf16 v[142:145], v[236:239], v[72:75], 0
	ds_read_b128 v[236:239], v151 offset:37888
	v_mfma_f32_16x16x32_bf16 v[72:75], v[146:149], v[72:75], 0
	v_cvt_pk_bf16_f32 v146, v212, v214
	v_cvt_pk_bf16_f32 v147, v217, v222
	v_cvt_pk_bf16_f32 v148, v225, v227
	v_cvt_pk_bf16_f32 v149, v228, v229
	s_nop 1
	v_mfma_f32_16x16x32_bf16 v[134:137], v[160:163], v[146:149], v[134:137]
	v_mfma_f32_16x16x32_bf16 v[138:141], v[240:243], v[146:149], v[138:141]
	ds_read_b128 v[240:243], v151 offset:56832
	s_waitcnt lgkmcnt(1)
	v_mfma_f32_16x16x32_bf16 v[142:145], v[236:239], v[146:149], v[142:145]
	s_waitcnt lgkmcnt(0)
; template <bool UPFRONT, class KP, class VP, class MOD>
; __device__ __forceinline__ void attn16(const bf16x8 (&qf)[2], KP kptr, VP vptr, MOD mod, bf16_t* outp  , int fr, int fq) {
;     ...
;     for (int s = 0; s < 8; ++s) {
;         u32x4 pw; pw.x = cvt_pk_bf16(st[2 * s][0], st[2 * s][1]); pw.y = cvt_pk_bf16(st[2 * s][2], st[2 * s][3]);
;         pw.z = cvt_pk_bf16(st[2 * s + 1][0], st[2 * s + 1][1]); pw.w = cvt_pk_bf16(st[2 * s + 1][2], st[2 * s + 1][3]);
;         bf16x8 pf; __builtin_memcpy(&pf, &pw, 16);
; #pragma unroll
;         for (int dt = 0; dt < 4; ++dt) { if (!UPFRONT) vf[s][dt] = vptr(16 * dt + fr, s); o[dt] = __builtin_amdgcn_mfma_f32_16x16x32_bf16(vf[s][dt], pf, o[dt], 0, 0, 0); }
;     }
;     const float inv = 1.0f / sum;
; #pragma unroll
;     for (int dt = 0; dt < 4; ++dt) { u32x2 w; w.x = cvt_pk_bf16(o[dt][0] * inv, o[dt][1] * inv); w.y = cvt_pk_bf16(o[dt][2] * inv, o[dt][3] * inv);
;         *(u32x2*)(outp + 16 * dt + 4 * fq) = w; }
	v_mfma_f32_16x16x32_bf16 v[72:75], v[240:243], v[146:149], v[72:75]
	v_cvt_pk_bf16_f32 v146, v150, v164
	v_add3_u32 v150, v210, s0, v190
	ds_read_b128 v[236:239], v150
	ds_read_b128 v[240:243], v150 offset:18944
	v_cvt_pk_bf16_f32 v147, v168, v213
	v_cvt_pk_bf16_f32 v148, v215, v218
	v_cvt_pk_bf16_f32 v149, v219, v226
	s_lshl_b32 s0, s29, 7
	s_waitcnt lgkmcnt(1)
	v_mfma_f32_16x16x32_bf16 v[134:137], v[236:239], v[146:149], v[134:137]
	ds_read_b128 v[236:239], v150 offset:37888
	s_waitcnt lgkmcnt(1)
	v_mfma_f32_16x16x32_bf16 v[138:141], v[240:243], v[146:149], v[138:141]
	ds_read_b128 v[240:243], v150 offset:56832
	s_waitcnt lgkmcnt(1)
	v_mfma_f32_16x16x32_bf16 v[142:145], v[236:239], v[146:149], v[142:145]
	s_waitcnt lgkmcnt(0)
	v_mfma_f32_16x16x32_bf16 v[72:75], v[240:243], v[146:149], v[72:75]
	v_cvt_pk_bf16_f32 v146, v125, v128
	v_add3_u32 v125, v210, s0, v190
	ds_read_b128 v[236:239], v125
	ds_read_b128 v[240:243], v125 offset:18944
	v_cvt_pk_bf16_f32 v147, v130, v152
	v_cvt_pk_bf16_f32 v148, v166, v170
	v_cvt_pk_bf16_f32 v149, v211, v216
	s_lshl_b32 s0, s28, 7
	s_waitcnt lgkmcnt(1)
	v_mfma_f32_16x16x32_bf16 v[134:137], v[236:239], v[146:149], v[134:137]
	ds_read_b128 v[236:239], v125 offset:37888
	s_waitcnt lgkmcnt(1)
	v_mfma_f32_16x16x32_bf16 v[138:141], v[240:243], v[146:149], v[138:141]
	ds_read_b128 v[240:243], v125 offset:56832
	s_waitcnt lgkmcnt(1)
	v_mfma_f32_16x16x32_bf16 v[142:145], v[236:239], v[146:149], v[142:145]
	s_waitcnt lgkmcnt(0)
	v_mfma_f32_16x16x32_bf16 v[72:75], v[240:243], v[146:149], v[72:75]
	v_cvt_pk_bf16_f32 v146, v118, v120
	v_add3_u32 v118, v210, s0, v190
	ds_read_b128 v[236:239], v118
	ds_read_b128 v[240:243], v118 offset:18944
	v_cvt_pk_bf16_f32 v148, v127, v131
	v_cvt_pk_bf16_f32 v149, v132, v133
	v_cvt_pk_bf16_f32 v147, v122, v126
	s_lshl_b32 s0, s15, 7
	v_cvt_pk_bf16_f32 v120, v121, v123
	s_waitcnt lgkmcnt(1)
	v_mfma_f32_16x16x32_bf16 v[130:133], v[236:239], v[146:149], v[134:137]
	ds_read_b128 v[236:239], v118 offset:37888
	s_nop 2
	v_cvt_pk_bf16_f32 v121, v124, v129
	s_waitcnt lgkmcnt(1)
	v_mfma_f32_16x16x32_bf16 v[134:137], v[240:243], v[146:149], v[138:141]
	ds_read_b128 v[240:243], v118 offset:56832
	s_nop 2
	s_waitcnt lgkmcnt(1)
	v_mfma_f32_16x16x32_bf16 v[138:141], v[236:239], v[146:149], v[142:145]
	s_nop 2
	v_cvt_pk_bf16_f32 v118, v110, v113
	v_add3_u32 v110, v210, s0, v190
	ds_read_b128 v[236:239], v110
	ds_read_b128 v[126:129], v110 offset:18944
	s_waitcnt lgkmcnt(1)
	v_mfma_f32_16x16x32_bf16 v[122:125], v[236:239], v[118:121], v[130:133]
	ds_read_b128 v[236:239], v110 offset:37888
	s_nop 2
	s_lshl_b32 s0, s14, 7
	v_add3_u32 v107, v210, s0, v190
	s_waitcnt lgkmcnt(1)
	v_mfma_f32_16x16x32_bf16 v[126:129], v[126:129], v[118:121], v[134:137]
	s_lshl_b32 s0, s6, 7
	s_nop 1
	ds_read_b128 v[134:137], v110 offset:56832
	v_mfma_f32_16x16x32_bf16 v[72:75], v[240:243], v[146:149], v[72:75]
	ds_read_b128 v[240:243], v107
	v_cvt_pk_bf16_f32 v110, v112, v114
	s_waitcnt lgkmcnt(2)
	v_mfma_f32_16x16x32_bf16 v[130:133], v[236:239], v[118:121], v[138:141]
	ds_read_b128 v[236:239], v107 offset:18944
	s_waitcnt lgkmcnt(2)
	v_mfma_f32_16x16x32_bf16 v[72:75], v[134:137], v[118:121], v[72:75]
	s_waitcnt lgkmcnt(1)
	v_mfma_f32_16x16x32_bf16 v[112:115], v[240:243], v[108:111], v[122:125]
	ds_read_b128 v[240:243], v107 offset:37888
	s_waitcnt lgkmcnt(1)
	v_mfma_f32_16x16x32_bf16 v[116:119], v[236:239], v[108:111], v[126:129]
	ds_read_b128 v[236:239], v107 offset:56832
	s_nop 0
	s_nop 0
	s_waitcnt lgkmcnt(1)
	v_mfma_f32_16x16x32_bf16 v[120:123], v[240:243], v[108:111], v[130:133]
	s_waitcnt lgkmcnt(0)
	v_mfma_f32_16x16x32_bf16 v[72:75], v[236:239], v[108:111], v[72:75]
	v_cvt_pk_bf16_f32 v108, v78, v79
	v_add3_u32 v78, v210, s0, v190
	ds_read_b128 v[240:243], v78
	ds_read_b128 v[236:239], v78 offset:18944
	v_cvt_pk_bf16_f32 v109, v99, v102
	v_cvt_pk_bf16_f32 v110, v103, v104
	v_cvt_pk_bf16_f32 v111, v105, v106
	v_div_scale_f32 v77, s[0:1], v76, v76, 1.0
	s_waitcnt lgkmcnt(1)
	v_mfma_f32_16x16x32_bf16 v[102:105], v[240:243], v[108:111], v[112:115]
	ds_read_b128 v[240:243], v78 offset:37888
	s_nop 2
	s_waitcnt lgkmcnt(1)
	v_mfma_f32_16x16x32_bf16 v[112:115], v[236:239], v[108:111], v[116:119]
	ds_read_b128 v[236:239], v78 offset:56832
	s_nop 2
	s_waitcnt lgkmcnt(1)
	v_mfma_f32_16x16x32_bf16 v[116:119], v[240:243], v[108:111], v[120:123]
	s_nop 2
	v_rcp_f32_e32 v78, v77
	s_waitcnt lgkmcnt(0)
	v_mfma_f32_16x16x32_bf16 v[72:75], v[236:239], v[108:111], v[72:75]
	v_fma_f32 v79, -v77, v78, 1.0
	v_fmac_f32_e32 v78, v79, v78
	v_div_scale_f32 v79, vcc, 1.0, v76, 1.0
	v_mul_f32_e32 v99, v79, v78
	v_fma_f32 v106, -v77, v99, v79
	v_fmac_f32_e32 v99, v106, v78
	v_fma_f32 v77, -v77, v99, v79
	v_div_fmas_f32 v77, v77, v78, v99
	v_div_fixup_f32 v99, v77, v76, 1.0
	v_mul_f32_e32 v78, v102, v99
	v_mul_f32_e32 v79, v103, v99
	v_lshl_add_u64 v[76:77], v[94:95], 0, v[100:101]
	v_cvt_pk_bf16_f32 v78, v78, v79
	v_mul_f32_e32 v79, v104, v99
	v_mul_f32_e32 v100, v105, v99
	v_cvt_pk_bf16_f32 v79, v79, v100
	global_store_dwordx2 v[76:77], v[78:79], off
	v_mul_f32_e32 v78, v112, v99
	v_mul_f32_e32 v79, v113, v99
	v_cvt_pk_bf16_f32 v78, v78, v79
	v_mul_f32_e32 v79, v114, v99
	v_mul_f32_e32 v100, v115, v99
	v_cvt_pk_bf16_f32 v79, v79, v100
	global_store_dwordx2 v[76:77], v[78:79], off offset:32
	v_mul_f32_e32 v78, v116, v99
	v_mul_f32_e32 v79, v117, v99
	v_mul_f32_e32 v72, v72, v99
	v_mul_f32_e32 v73, v73, v99
	v_cvt_pk_bf16_f32 v78, v78, v79
	v_mul_f32_e32 v79, v118, v99
	v_mul_f32_e32 v100, v119, v99
	v_cvt_pk_bf16_f32 v72, v72, v73
	v_mul_f32_e32 v73, v74, v99
	v_mul_f32_e32 v74, v75, v99
	v_cvt_pk_bf16_f32 v79, v79, v100
	v_cvt_pk_bf16_f32 v73, v73, v74
	global_store_dwordx2 v[76:77], v[78:79], off offset:64
	global_store_dwordx2 v[76:77], v[72:73], off offset:96
	s_add_i32 s74, s74, 2
	s_add_i32 s52, s52, -2
	s_cmp_eq_u32 s74, 8
	v_add_u32_e32 v98, 0x80, v98
	s_cbranch_scc1 .LBB0_126
	s_mov_b32 s0, s75
	s_branch .LBB0_128

; __device__ __forceinline__ void ret_out(const bf16_t* proj, const float* cosT, const float* sinT, const float* decay, const float* gn_g, const float* gn_b,
;                         const bf16_t* states, bf16_t* mix, unsigned char* lds, int tid, int bx) {
;     ...
;         for (int s = 0; s < 4; ++s) {
;             f32x4 st2[2];
; #pragma unroll
;             for (int pp = 0; pp < 2; ++pp) {
;                 const bf16_t* kr = Kl + (32 * s + 8 * (fr >> 2) + 4 * pp + (fr & 3)) * LP + 8 * fq;
;                 f32x4 a = (f32x4){0.f, 0.f, 0.f, 0.f};
; #pragma unroll
;                 for (int ks = 0; ks < 4; ++ks) a = __builtin_amdgcn_mfma_f32_16x16x32_bf16(*(const bf16x8*)(kr + 32 * ks), qf[ks], a, 0, 0, 0);
; #pragma unroll
;                 for (int r = 0; r < 4; ++r) { const int sk = 32 * s + 8 * fq + 4 * pp + r, diff = cq - sk;
;                     const float df = (float)diff;
;                     const float dd = __builtin_amdgcn_exp2f(fminf(lgf2 * df, -lgb2 * df)) + fmaxf(1.0f - fabsf(df), 0.0f);
;                     a[r] *= dd * 0.08838834764831845f; }
;                 st2[pp] = a;
;             }
;             const u32x4 pw = (u32x4){cvt_pk_bf16(st2[0][0], st2[0][1]), cvt_pk_bf16(st2[0][2], st2[0][3]), cvt_pk_bf16(st2[1][0], st2[1][1]), cvt_pk_bf16(st2[1][2], st2[1][3])};
;             __builtin_memcpy(&pf[s], &pw, 16);
;         }
.Lro_nopf:
	v_lshlrev_b32_e32 v142, 16, v69
	v_cvt_pk_bf16_f32 v11, v16, v17
	v_lshlrev_b32_e32 v16, 1, v22
	v_and_b32_e32 v17, 3, v22
	v_and_or_b32 v16, v16, 24, v17
	v_mul_u32_u24_e32 v16, 0x110, v16
	v_add3_u32 v52, 0, v62, v16
	ds_read_b128 v[220:223], v52
	ds_read_b128 v[224:227], v52 offset:64
	ds_read_b128 v[228:231], v52 offset:1152
	ds_read_b128 v[232:235], v52 offset:128
	ds_read_b128 v[236:239], v52 offset:192
	ds_read_b128 v[240:243], v52 offset:1088
	s_waitcnt lgkmcnt(5)
	v_mfma_f32_16x16x32_bf16 v[16:19], v[220:223], v[4:7], 0
	ds_read_b128 v[220:223], v52 offset:1216
	v_and_b32_e32 v143, 0xffff0000, v69
	v_lshlrev_b32_e32 v146, 16, v68
	s_waitcnt lgkmcnt(5)
	v_mfma_f32_16x16x32_bf16 v[16:19], v[224:227], v[12:15], v[16:19]
	ds_read_b128 v[224:227], v52 offset:1280
	v_and_b32_e32 v147, 0xffff0000, v68
	s_waitcnt lgkmcnt(4)
	v_mfma_f32_16x16x32_bf16 v[16:19], v[232:235], v[0:3], v[16:19]
	ds_read_b128 v[232:235], v52 offset:8768
	s_waitcnt lgkmcnt(4)
	v_mfma_f32_16x16x32_bf16 v[16:19], v[236:239], v[8:11], v[16:19]
	ds_read_b128 v[236:239], v52 offset:8704
	v_cvt_f32_i32_e32 v20, v53
	v_mul_f32_e32 v21, v87, v20
	v_mul_f32_e32 v22, v63, v20
	v_sub_f32_e64 v20, 1.0, |v20|
	v_max_f32_e32 v30, 0, v20
	v_xad_u32 v20, v154, -1, v86
	v_cvt_f32_i32_e32 v20, v20
	v_min_f32_e32 v21, v21, v22
	v_exp_f32_e32 v28, v21
	v_mul_f32_e32 v21, v87, v20
	v_mul_f32_e32 v22, v63, v20
	v_sub_f32_e64 v20, 1.0, |v20|
	v_max_f32_e32 v31, 0, v20
	v_add_u32_e32 v20, -2, v53
	v_cvt_f32_i32_e32 v20, v20
	v_min_f32_e32 v21, v21, v22
	v_exp_f32_e32 v29, v21
	v_mul_f32_e32 v21, v87, v20
	v_mul_f32_e32 v22, v63, v20
	v_sub_f32_e64 v20, 1.0, |v20|
	v_max_f32_e32 v34, 0, v20
	v_add_u32_e32 v20, -3, v53
	v_cvt_f32_i32_e32 v20, v20
	v_min_f32_e32 v21, v21, v22
	v_exp_f32_e32 v32, v21
	v_pk_add_f32 v[28:29], v[28:29], v[30:31]
	v_mul_f32_e32 v21, v87, v20
	v_mul_f32_e32 v22, v63, v20
	v_min_f32_e32 v21, v21, v22
	v_sub_f32_e64 v20, 1.0, |v20|
	v_exp_f32_e32 v33, v21
	v_max_f32_e32 v35, 0, v20
	s_waitcnt lgkmcnt(4)
	v_mfma_f32_16x16x32_bf16 v[20:23], v[240:243], v[4:7], 0
	ds_read_b128 v[240:243], v52 offset:8832
	v_mul_f32_e64 v28, v28, s54
	v_mul_f32_e64 v29, v29, s54
	v_pk_mul_f32 v[16:17], v[28:29], v[16:17]
	v_mfma_f32_16x16x32_bf16 v[20:23], v[228:231], v[12:15], v[20:23]
	ds_read_b128 v[228:231], v52 offset:8896
	v_pk_add_f32 v[28:29], v[32:33], v[34:35]
	v_cvt_pk_bf16_f32 v16, v16, v17
	s_waitcnt lgkmcnt(5)
	v_mfma_f32_16x16x32_bf16 v[20:23], v[220:223], v[0:3], v[20:23]
	ds_read_b128 v[220:223], v52 offset:9856
	v_pk_mul_f32 v[28:29], v[28:29], s[54:55] op_sel_hi:[1,0]
	s_waitcnt lgkmcnt(5)
	v_mfma_f32_16x16x32_bf16 v[20:23], v[224:227], v[8:11], v[20:23]
	ds_read_b128 v[224:227], v52 offset:9792
	v_add_u32_e32 v24, -4, v53
	v_cvt_f32_i32_e32 v25, v24
	v_pk_mul_f32 v[18:19], v[28:29], v[18:19]
	v_or_b32_e32 v28, 32, v154
	v_cvt_pk_bf16_f32 v17, v18, v19
	v_mul_f32_e32 v24, v87, v25
	v_mul_f32_e32 v26, v63, v25
	v_sub_f32_e64 v25, 1.0, |v25|
	v_min_f32_e32 v24, v24, v26
	v_max_f32_e32 v26, 0, v25
	v_add_u32_e32 v25, -5, v53
	v_cvt_f32_i32_e32 v27, v25
	v_exp_f32_e32 v24, v24
	v_mul_f32_e32 v25, v87, v27
	v_mul_f32_e32 v36, v63, v27
	v_min_f32_e32 v25, v25, v36
	v_add_u32_e32 v36, -6, v53
	v_cvt_f32_i32_e32 v37, v36
	v_exp_f32_e32 v25, v25
	v_sub_f32_e64 v27, 1.0, |v27|
	v_max_f32_e32 v27, 0, v27
	v_mul_f32_e32 v36, v87, v37
	v_mul_f32_e32 v38, v63, v37
	v_sub_f32_e64 v37, 1.0, |v37|
	v_min_f32_e32 v36, v36, v38
	v_max_f32_e32 v38, 0, v37
	v_add_u32_e32 v37, -7, v53
	v_cvt_f32_i32_e32 v39, v37
	v_exp_f32_e32 v36, v36
	v_pk_add_f32 v[18:19], v[24:25], v[26:27]
	v_mul_f32_e32 v37, v87, v39
	v_mul_f32_e32 v40, v63, v39
	v_min_f32_e32 v37, v37, v40
	v_exp_f32_e32 v37, v37
	v_sub_f32_e64 v39, 1.0, |v39|
	v_max_f32_e32 v39, 0, v39
	v_pk_mul_f32 v[18:19], v[18:19], s[54:55] op_sel_hi:[1,0]
	s_nop 0
	v_pk_mul_f32 v[18:19], v[18:19], v[20:21]
	v_pk_add_f32 v[20:21], v[36:37], v[38:39]
	v_cvt_pk_bf16_f32 v18, v18, v19
	v_pk_mul_f32 v[20:21], v[20:21], s[54:55] op_sel_hi:[1,0]
	s_nop 0
	v_pk_mul_f32 v[20:21], v[20:21], v[22:23]
	s_nop 0
	v_cvt_pk_bf16_f32 v19, v20, v21
	s_waitcnt lgkmcnt(4)
	v_mfma_f32_16x16x32_bf16 v[20:23], v[236:239], v[4:7], 0
	ds_read_b128 v[236:239], v52 offset:9920
	v_mfma_f32_16x16x32_bf16 v[20:23], v[232:235], v[12:15], v[20:23]
	ds_read_b128 v[232:235], v52 offset:9984
	s_waitcnt lgkmcnt(5)
	v_mfma_f32_16x16x32_bf16 v[20:23], v[240:243], v[0:3], v[20:23]
	ds_read_b128 v[240:243], v52 offset:17472
	s_waitcnt lgkmcnt(5)
	v_mfma_f32_16x16x32_bf16 v[20:23], v[228:231], v[8:11], v[20:23]
	ds_read_b128 v[228:231], v52 offset:17408
	v_sub_u32_e32 v24, v86, v28
	v_cvt_f32_i32_e32 v24, v24
	v_mul_f32_e32 v25, v87, v24
	v_mul_f32_e32 v26, v63, v24
	v_sub_f32_e64 v24, 1.0, |v24|
	v_max_f32_e32 v34, 0, v24
	v_subrev_u32_e32 v24, 33, v53
	v_cvt_f32_i32_e32 v24, v24
	v_min_f32_e32 v25, v25, v26
	v_exp_f32_e32 v32, v25
	v_mul_f32_e32 v25, v87, v24
	v_mul_f32_e32 v26, v63, v24
	v_sub_f32_e64 v24, 1.0, |v24|
	v_max_f32_e32 v35, 0, v24
	v_subrev_u32_e32 v24, 34, v53
	v_cvt_f32_i32_e32 v24, v24
	v_min_f32_e32 v25, v25, v26
	v_exp_f32_e32 v33, v25
	v_mul_f32_e32 v25, v87, v24
	v_mul_f32_e32 v26, v63, v24
	v_sub_f32_e64 v24, 1.0, |v24|
	v_max_f32_e32 v38, 0, v24
	v_subrev_u32_e32 v24, 35, v53
	v_cvt_f32_i32_e32 v24, v24
	v_min_f32_e32 v25, v25, v26
	v_exp_f32_e32 v36, v25
	v_pk_add_f32 v[32:33], v[32:33], v[34:35]
	v_mul_f32_e32 v25, v87, v24
	v_mul_f32_e32 v26, v63, v24
	v_min_f32_e32 v25, v25, v26
	v_sub_f32_e64 v24, 1.0, |v24|
	v_exp_f32_e32 v37, v25
	v_max_f32_e32 v39, 0, v24
	s_waitcnt lgkmcnt(4)
; __device__ __forceinline__ void ret_out(const bf16_t* proj, const float* cosT, const float* sinT, const float* decay, const float* gn_g, const float* gn_b,
;                         const bf16_t* states, bf16_t* mix, unsigned char* lds, int tid, int bx) {
;     ...
;         for (int s = 0; s < 4; ++s) {
;             f32x4 st2[2];
; #pragma unroll
;             for (int pp = 0; pp < 2; ++pp) {
;                 const bf16_t* kr = Kl + (32 * s + 8 * (fr >> 2) + 4 * pp + (fr & 3)) * LP + 8 * fq;
;                 f32x4 a = (f32x4){0.f, 0.f, 0.f, 0.f};
; #pragma unroll
;                 for (int ks = 0; ks < 4; ++ks) a = __builtin_amdgcn_mfma_f32_16x16x32_bf16(*(const bf16x8*)(kr + 32 * ks), qf[ks], a, 0, 0, 0);
; #pragma unroll
;                 for (int r = 0; r < 4; ++r) { const int sk = 32 * s + 8 * fq + 4 * pp + r, diff = cq - sk;
;                     const float df = (float)diff;
;                     const float dd = __builtin_amdgcn_exp2f(fminf(lgf2 * df, -lgb2 * df)) + fmaxf(1.0f - fabsf(df), 0.0f);
;                     a[r] *= dd * 0.08838834764831845f; }
;                 st2[pp] = a;
;             }
;             const u32x4 pw = (u32x4){cvt_pk_bf16(st2[0][0], st2[0][1]), cvt_pk_bf16(st2[0][2], st2[0][3]), cvt_pk_bf16(st2[1][0], st2[1][1]), cvt_pk_bf16(st2[1][2], st2[1][3])};
;             __builtin_memcpy(&pf[s], &pw, 16);
;         }
	v_mfma_f32_16x16x32_bf16 v[24:27], v[224:227], v[4:7], 0
	ds_read_b128 v[224:227], v52 offset:17536
	v_mul_f32_e64 v32, v32, s54
	v_mul_f32_e64 v33, v33, s54
	v_pk_mul_f32 v[20:21], v[32:33], v[20:21]
	v_mfma_f32_16x16x32_bf16 v[24:27], v[220:223], v[12:15], v[24:27]
	ds_read_b128 v[220:223], v52 offset:17600
	v_pk_add_f32 v[32:33], v[36:37], v[38:39]
	v_cvt_pk_bf16_f32 v20, v20, v21
	s_waitcnt lgkmcnt(5)
	v_mfma_f32_16x16x32_bf16 v[24:27], v[236:239], v[0:3], v[24:27]
	ds_read_b128 v[236:239], v52 offset:18560
	v_pk_mul_f32 v[32:33], v[32:33], s[54:55] op_sel_hi:[1,0]
	s_waitcnt lgkmcnt(5)
	v_mfma_f32_16x16x32_bf16 v[24:27], v[232:235], v[8:11], v[24:27]
	ds_read_b128 v[232:235], v52 offset:18496
	v_subrev_u32_e32 v28, 36, v53
	v_cvt_f32_i32_e32 v29, v28
	v_pk_mul_f32 v[22:23], v[32:33], v[22:23]
	v_or_b32_e32 v32, 64, v154
	v_cvt_pk_bf16_f32 v21, v22, v23
	v_mul_f32_e32 v28, v87, v29
	v_mul_f32_e32 v30, v63, v29
	v_sub_f32_e64 v29, 1.0, |v29|
	v_min_f32_e32 v28, v28, v30
	v_max_f32_e32 v30, 0, v29
	v_subrev_u32_e32 v29, 37, v53
	v_cvt_f32_i32_e32 v31, v29
	v_exp_f32_e32 v28, v28
	v_mul_f32_e32 v29, v87, v31
	v_mul_f32_e32 v40, v63, v31
	v_min_f32_e32 v29, v29, v40
	v_subrev_u32_e32 v40, 38, v53
	v_cvt_f32_i32_e32 v41, v40
	v_exp_f32_e32 v29, v29
	v_sub_f32_e64 v31, 1.0, |v31|
	v_max_f32_e32 v31, 0, v31
	v_mul_f32_e32 v40, v87, v41
	v_mul_f32_e32 v42, v63, v41
	v_sub_f32_e64 v41, 1.0, |v41|
	v_min_f32_e32 v40, v40, v42
	v_max_f32_e32 v42, 0, v41
	v_subrev_u32_e32 v41, 39, v53
	v_cvt_f32_i32_e32 v43, v41
	v_exp_f32_e32 v40, v40
	v_pk_add_f32 v[22:23], v[28:29], v[30:31]
	v_mul_f32_e32 v41, v87, v43
	v_mul_f32_e32 v44, v63, v43
	v_min_f32_e32 v41, v41, v44
	v_exp_f32_e32 v41, v41
	v_sub_f32_e64 v43, 1.0, |v43|
	v_max_f32_e32 v43, 0, v43
	v_pk_mul_f32 v[22:23], v[22:23], s[54:55] op_sel_hi:[1,0]
	s_nop 0
	v_pk_mul_f32 v[22:23], v[22:23], v[24:25]
	v_pk_add_f32 v[24:25], v[40:41], v[42:43]
	v_cvt_pk_bf16_f32 v22, v22, v23
	v_pk_mul_f32 v[24:25], v[24:25], s[54:55] op_sel_hi:[1,0]
	s_nop 0
	v_pk_mul_f32 v[24:25], v[24:25], v[26:27]
	s_nop 0
	v_cvt_pk_bf16_f32 v23, v24, v25
	s_waitcnt lgkmcnt(4)
	v_mfma_f32_16x16x32_bf16 v[24:27], v[228:231], v[4:7], 0
	ds_read_b128 v[228:231], v52 offset:18624
	v_mfma_f32_16x16x32_bf16 v[24:27], v[240:243], v[12:15], v[24:27]
	ds_read_b128 v[240:243], v52 offset:18688
	s_waitcnt lgkmcnt(5)
	v_mfma_f32_16x16x32_bf16 v[24:27], v[224:227], v[0:3], v[24:27]
	ds_read_b128 v[224:227], v52 offset:26176
	s_waitcnt lgkmcnt(5)
	v_mfma_f32_16x16x32_bf16 v[24:27], v[220:223], v[8:11], v[24:27]
	ds_read_b128 v[220:223], v52 offset:26112
	v_sub_u32_e32 v28, v86, v32
	v_cvt_f32_i32_e32 v28, v28
	v_mul_f32_e32 v29, v87, v28
	v_mul_f32_e32 v30, v63, v28
	v_sub_f32_e64 v28, 1.0, |v28|
	v_max_f32_e32 v38, 0, v28
	v_add_u32_e32 v28, 0xffffffbf, v53
	v_cvt_f32_i32_e32 v28, v28
	v_min_f32_e32 v29, v29, v30
	v_exp_f32_e32 v36, v29
	v_mul_f32_e32 v29, v87, v28
	v_mul_f32_e32 v30, v63, v28
	v_sub_f32_e64 v28, 1.0, |v28|
	v_max_f32_e32 v39, 0, v28
	v_add_u32_e32 v28, 0xffffffbe, v53
	v_cvt_f32_i32_e32 v28, v28
	v_min_f32_e32 v29, v29, v30
	v_exp_f32_e32 v37, v29
	v_mul_f32_e32 v29, v87, v28
	v_mul_f32_e32 v30, v63, v28
	v_sub_f32_e64 v28, 1.0, |v28|
	v_max_f32_e32 v42, 0, v28
	v_add_u32_e32 v28, 0xffffffbd, v53
	v_cvt_f32_i32_e32 v28, v28
	v_min_f32_e32 v29, v29, v30
	v_exp_f32_e32 v40, v29
	v_pk_add_f32 v[36:37], v[36:37], v[38:39]
	v_mul_f32_e32 v29, v87, v28
	v_mul_f32_e32 v30, v63, v28
	v_min_f32_e32 v29, v29, v30
	v_sub_f32_e64 v28, 1.0, |v28|
	v_exp_f32_e32 v41, v29
	v_max_f32_e32 v43, 0, v28
	s_waitcnt lgkmcnt(4)
	v_mfma_f32_16x16x32_bf16 v[28:31], v[232:235], v[4:7], 0
	ds_read_b128 v[232:235], v52 offset:26240
	v_mul_f32_e64 v36, v36, s54
	v_mul_f32_e64 v37, v37, s54
	v_pk_mul_f32 v[24:25], v[36:37], v[24:25]
	v_mfma_f32_16x16x32_bf16 v[28:31], v[236:239], v[12:15], v[28:31]
	ds_read_b128 v[236:239], v52 offset:26304
	s_waitcnt lgkmcnt(5)
	v_mfma_f32_16x16x32_bf16 v[28:31], v[228:231], v[0:3], v[28:31]
	ds_read_b128 v[228:231], v52 offset:27264
	s_waitcnt lgkmcnt(5)
	v_mfma_f32_16x16x32_bf16 v[28:31], v[240:243], v[8:11], v[28:31]
	ds_read_b128 v[240:243], v52 offset:27200
	v_add_u32_e32 v32, 0xffffffbc, v53
	v_cvt_f32_i32_e32 v33, v32
	v_mul_f32_e32 v32, v87, v33
	v_mul_f32_e32 v34, v63, v33
	v_sub_f32_e64 v33, 1.0, |v33|
	v_min_f32_e32 v32, v32, v34
	v_max_f32_e32 v34, 0, v33
	v_add_u32_e32 v33, 0xffffffbb, v53
	v_cvt_f32_i32_e32 v35, v33
	v_exp_f32_e32 v32, v32
	v_mul_f32_e32 v33, v87, v35
	v_mul_f32_e32 v44, v63, v35
	v_min_f32_e32 v33, v33, v44
	v_add_u32_e32 v44, 0xffffffba, v53
	v_cvt_f32_i32_e32 v45, v44
	v_exp_f32_e32 v33, v33
	v_sub_f32_e64 v35, 1.0, |v35|
	v_max_f32_e32 v35, 0, v35
	v_mul_f32_e32 v44, v87, v45
	v_mul_f32_e32 v46, v63, v45
	v_sub_f32_e64 v45, 1.0, |v45|
	v_min_f32_e32 v44, v44, v46
	v_max_f32_e32 v46, 0, v45
	v_add_u32_e32 v45, 0xffffffb9, v53
	v_cvt_f32_i32_e32 v47, v45
	v_exp_f32_e32 v44, v44
	v_mul_f32_e32 v45, v87, v47
	v_mul_f32_e32 v48, v63, v47
	v_min_f32_e32 v45, v45, v48
	v_cvt_pk_bf16_f32 v48, v24, v25
	v_pk_add_f32 v[24:25], v[40:41], v[42:43]
	v_exp_f32_e32 v45, v45
	v_pk_mul_f32 v[24:25], v[24:25], s[54:55] op_sel_hi:[1,0]
	v_sub_f32_e64 v47, 1.0, |v47|
	v_pk_mul_f32 v[24:25], v[24:25], v[26:27]
	v_max_f32_e32 v47, 0, v47
	v_cvt_pk_bf16_f32 v49, v24, v25
	v_pk_add_f32 v[24:25], v[32:33], v[34:35]
	v_or_b32_e32 v32, 0x60, v154
	v_pk_mul_f32 v[24:25], v[24:25], s[54:55] op_sel_hi:[1,0]
	s_nop 0
	v_pk_mul_f32 v[24:25], v[24:25], v[28:29]
	s_nop 0
	v_cvt_pk_bf16_f32 v50, v24, v25
	v_pk_add_f32 v[24:25], v[44:45], v[46:47]
	s_nop 0
	v_pk_mul_f32 v[24:25], v[24:25], s[54:55] op_sel_hi:[1,0]
	s_nop 0
	v_pk_mul_f32 v[24:25], v[24:25], v[30:31]
	v_cvt_pk_bf16_f32 v51, v24, v25
	s_waitcnt lgkmcnt(4)
; __device__ __forceinline__ void ret_out(const bf16_t* proj, const float* cosT, const float* sinT, const float* decay, const float* gn_g, const float* gn_b,
;                         const bf16_t* states, bf16_t* mix, unsigned char* lds, int tid, int bx) {
;     ...
;         for (int s = 0; s < 4; ++s) {
;             f32x4 st2[2];
; #pragma unroll
;             for (int pp = 0; pp < 2; ++pp) {
;                 const bf16_t* kr = Kl + (32 * s + 8 * (fr >> 2) + 4 * pp + (fr & 3)) * LP + 8 * fq;
;                 f32x4 a = (f32x4){0.f, 0.f, 0.f, 0.f};
; #pragma unroll
;                 for (int ks = 0; ks < 4; ++ks) a = __builtin_amdgcn_mfma_f32_16x16x32_bf16(*(const bf16x8*)(kr + 32 * ks), qf[ks], a, 0, 0, 0);
; #pragma unroll
;                 for (int r = 0; r < 4; ++r) { const int sk = 32 * s + 8 * fq + 4 * pp + r, diff = cq - sk;
;                     const float df = (float)diff;
;                     const float dd = __builtin_amdgcn_exp2f(fminf(lgf2 * df, -lgb2 * df)) + fmaxf(1.0f - fabsf(df), 0.0f);
;                     a[r] *= dd * 0.08838834764831845f; }
;                 st2[pp] = a;
;             }
;             const u32x4 pw = (u32x4){cvt_pk_bf16(st2[0][0], st2[0][1]), cvt_pk_bf16(st2[0][2], st2[0][3]), cvt_pk_bf16(st2[1][0], st2[1][1]), cvt_pk_bf16(st2[1][2], st2[1][3])};
;             __builtin_memcpy(&pf[s], &pw, 16);
;         }
;         f32x4 acc[8];
; #pragma unroll
;         for (int e8 = 0; e8 < 8; ++e8) acc[e8] = (f32x4){0.f, 0.f, 0.f, 0.f};
; #pragma unroll
;         for (int s = 0; s < 4; ++s)
; #pragma unroll
;             for (int e8 = 0; e8 < 8; ++e8) acc[e8] = __builtin_amdgcn_mfma_f32_16x16x32_bf16(*(const bf16x8*)(Vl + (16 * e8 + fr) * LP + ((32 * s + 8 * fq) ^ ((e8 & 3) << 4))), pf[s], acc[e8], 0, 0, 0);
	v_mfma_f32_16x16x32_bf16 v[24:27], v[220:223], v[4:7], 0
	ds_read_b128 v[220:223], v52 offset:27328
	v_mfma_f32_16x16x32_bf16 v[24:27], v[224:227], v[12:15], v[24:27]
	ds_read_b128 v[224:227], v52 offset:27392
	s_waitcnt lgkmcnt(5)
	v_mfma_f32_16x16x32_bf16 v[24:27], v[232:235], v[0:3], v[24:27]
	s_waitcnt lgkmcnt(4)
	v_mfma_f32_16x16x32_bf16 v[24:27], v[236:239], v[8:11], v[24:27]
	v_sub_u32_e32 v28, v86, v32
	v_cvt_f32_i32_e32 v28, v28
	v_mul_f32_e32 v29, v87, v28
	v_mul_f32_e32 v30, v63, v28
	v_sub_f32_e64 v28, 1.0, |v28|
	v_max_f32_e32 v38, 0, v28
	v_add_u32_e32 v28, 0xffffff9f, v53
	v_cvt_f32_i32_e32 v28, v28
	v_min_f32_e32 v29, v29, v30
	v_exp_f32_e32 v36, v29
	v_mul_f32_e32 v29, v87, v28
	v_mul_f32_e32 v30, v63, v28
	v_sub_f32_e64 v28, 1.0, |v28|
	v_max_f32_e32 v39, 0, v28
	v_add_u32_e32 v28, 0xffffff9e, v53
	v_cvt_f32_i32_e32 v28, v28
	v_min_f32_e32 v29, v29, v30
	v_exp_f32_e32 v37, v29
	v_mul_f32_e32 v29, v87, v28
	v_mul_f32_e32 v30, v63, v28
	v_sub_f32_e64 v28, 1.0, |v28|
	v_max_f32_e32 v42, 0, v28
	v_add_u32_e32 v28, 0xffffff9d, v53
	v_cvt_f32_i32_e32 v28, v28
	v_min_f32_e32 v29, v29, v30
	v_exp_f32_e32 v40, v29
	v_pk_add_f32 v[36:37], v[36:37], v[38:39]
	v_mul_f32_e32 v29, v87, v28
	v_mul_f32_e32 v30, v63, v28
	v_min_f32_e32 v29, v29, v30
	v_sub_f32_e64 v28, 1.0, |v28|
	v_exp_f32_e32 v41, v29
	v_max_f32_e32 v43, 0, v28
	s_waitcnt lgkmcnt(2)
	v_mfma_f32_16x16x32_bf16 v[28:31], v[240:243], v[4:7], 0
	v_mul_f32_e64 v36, v36, s54
	v_mul_f32_e64 v37, v37, s54
	v_pk_mul_f32 v[24:25], v[36:37], v[24:25]
	v_mfma_f32_16x16x32_bf16 v[28:31], v[228:231], v[12:15], v[28:31]
	v_pk_add_f32 v[36:37], v[40:41], v[42:43]
	v_cvt_pk_bf16_f32 v24, v24, v25
	s_waitcnt lgkmcnt(1)
	v_mfma_f32_16x16x32_bf16 v[28:31], v[220:223], v[0:3], v[28:31]
	v_pk_mul_f32 v[36:37], v[36:37], s[54:55] op_sel_hi:[1,0]
	s_waitcnt lgkmcnt(0)
	v_mfma_f32_16x16x32_bf16 v[28:31], v[224:227], v[8:11], v[28:31]
	v_add_u32_e32 v32, 0xffffff9c, v53
	v_cvt_f32_i32_e32 v33, v32
	v_pk_mul_f32 v[26:27], v[36:37], v[26:27]
	v_mul_f32_e32 v32, v87, v33
	v_mul_f32_e32 v34, v63, v33
	v_sub_f32_e64 v33, 1.0, |v33|
	v_min_f32_e32 v32, v32, v34
	v_max_f32_e32 v34, 0, v33
	v_add_u32_e32 v33, 0xffffff9b, v53
	v_cvt_f32_i32_e32 v35, v33
	v_exp_f32_e32 v32, v32
	v_cvt_pk_bf16_f32 v25, v26, v27
	v_mul_f32_e32 v33, v87, v35
	v_mul_f32_e32 v44, v63, v35
	v_min_f32_e32 v33, v33, v44
	v_add_u32_e32 v44, 0xffffff9a, v53
	v_cvt_f32_i32_e32 v45, v44
	v_exp_f32_e32 v33, v33
	v_sub_f32_e64 v35, 1.0, |v35|
	v_max_f32_e32 v35, 0, v35
	v_mul_f32_e32 v44, v87, v45
	v_mul_f32_e32 v46, v63, v45
	v_sub_f32_e64 v45, 1.0, |v45|
	v_min_f32_e32 v44, v44, v46
	v_max_f32_e32 v46, 0, v45
	v_add_u32_e32 v45, 0xffffff99, v53
	v_cvt_f32_i32_e32 v47, v45
	v_exp_f32_e32 v44, v44
	v_pk_add_f32 v[26:27], v[32:33], v[34:35]
	v_bitop3_b32 v53, v154, s0, v180 bitop3:0xc8
	v_mul_f32_e32 v45, v87, v47
	v_mul_f32_e32 v52, v63, v47
	v_min_f32_e32 v45, v45, v52
	v_exp_f32_e32 v45, v45
	v_sub_f32_e64 v47, 1.0, |v47|
	v_max_f32_e32 v47, 0, v47
	v_pk_mul_f32 v[26:27], v[26:27], s[54:55] op_sel_hi:[1,0]
	v_mad_u32_u24 v52, v83, s52, 0
	v_pk_mul_f32 v[26:27], v[26:27], v[28:29]
	v_pk_add_f32 v[28:29], v[44:45], v[46:47]
	v_add_u32_e32 v89, v52, v62
	v_pk_mul_f32 v[28:29], v[28:29], s[54:55] op_sel_hi:[1,0]
	v_xad_u32 v88, v62, 32, v52
	v_pk_mul_f32 v[28:29], v[28:29], v[30:31]
	v_cvt_pk_bf16_f32 v26, v26, v27
	v_cvt_pk_bf16_f32 v27, v28, v29
	ds_read_b128 v[28:31], v89 offset:34816
	ds_read_b128 v[36:39], v89 offset:43584
	ds_read_b128 v[32:35], v88 offset:39168
	ds_read_b128 v[40:43], v88 offset:47936
	ds_read_b128 v[44:47], v89 offset:52224
	ds_read_b128 v[90:93], v89 offset:60992
	ds_read_b128 v[54:57], v88 offset:56576
	ds_read_b128 v[94:97], v88 offset:65344
	s_waitcnt lgkmcnt(7)
	v_mfma_f32_16x16x32_bf16 v[28:31], v[28:31], v[16:19], 0
	s_lshl_b32 s0, s36, 9
	s_add_i32 s0, s0, 0
	s_cmpk_lt_i32 s49, 0x600
	s_waitcnt lgkmcnt(5)
	v_mfma_f32_16x16x32_bf16 v[32:35], v[32:35], v[16:19], 0
	v_mfma_f32_16x16x32_bf16 v[36:39], v[36:39], v[16:19], 0
	s_waitcnt lgkmcnt(4)
	v_mfma_f32_16x16x32_bf16 v[40:43], v[40:43], v[16:19], 0
	s_waitcnt lgkmcnt(3)
	v_mfma_f32_16x16x32_bf16 v[44:47], v[44:47], v[16:19], 0
	s_waitcnt lgkmcnt(1)
	v_mfma_f32_16x16x32_bf16 v[54:57], v[54:57], v[16:19], 0
	v_mfma_f32_16x16x32_bf16 v[90:93], v[90:93], v[16:19], 0
	s_waitcnt lgkmcnt(0)
	v_mfma_f32_16x16x32_bf16 v[16:19], v[94:97], v[16:19], 0
	ds_read_b128 v[94:97], v89 offset:34880
	ds_read_b128 v[220:223], v88 offset:39232
	ds_read_b128 v[224:227], v89 offset:43520
	ds_read_b128 v[228:231], v88 offset:47872
	ds_read_b128 v[232:235], v89 offset:52288
	ds_read_b128 v[236:239], v88 offset:56640
	ds_read_b128 v[240:243], v89 offset:60928
	s_waitcnt lgkmcnt(6)
	v_mfma_f32_16x16x32_bf16 v[28:31], v[94:97], v[20:23], v[28:31]
	ds_read_b128 v[94:97], v88 offset:65280
	s_waitcnt lgkmcnt(6)
	v_mfma_f32_16x16x32_bf16 v[32:35], v[220:223], v[20:23], v[32:35]
	s_waitcnt lgkmcnt(5)
	v_mfma_f32_16x16x32_bf16 v[36:39], v[224:227], v[20:23], v[36:39]
	s_waitcnt lgkmcnt(4)
	v_mfma_f32_16x16x32_bf16 v[40:43], v[228:231], v[20:23], v[40:43]
	s_waitcnt lgkmcnt(3)
	v_mfma_f32_16x16x32_bf16 v[44:47], v[232:235], v[20:23], v[44:47]
	s_waitcnt lgkmcnt(2)
	v_mfma_f32_16x16x32_bf16 v[54:57], v[236:239], v[20:23], v[54:57]
	s_waitcnt lgkmcnt(1)
	v_mfma_f32_16x16x32_bf16 v[90:93], v[240:243], v[20:23], v[90:93]
	s_waitcnt lgkmcnt(0)
	v_mfma_f32_16x16x32_bf16 v[16:19], v[94:97], v[20:23], v[16:19]
	ds_read_b128 v[220:223], v89 offset:34944
	ds_read_b128 v[224:227], v88 offset:39296
	ds_read_b128 v[228:231], v89 offset:43712
	ds_read_b128 v[232:235], v88 offset:48064
	ds_read_b128 v[236:239], v89 offset:52352
	ds_read_b128 v[240:243], v88 offset:56704
	s_waitcnt lgkmcnt(5)
; __device__ __forceinline__ void ret_out(const bf16_t* proj, const float* cosT, const float* sinT, const float* decay, const float* gn_g, const float* gn_b,
;                         const bf16_t* states, bf16_t* mix, unsigned char* lds, int tid, int bx) {
;     ...
;         f32x4 acc[8];
; #pragma unroll
;         for (int e8 = 0; e8 < 8; ++e8) acc[e8] = (f32x4){0.f, 0.f, 0.f, 0.f};
; #pragma unroll
;         for (int s = 0; s < 4; ++s)
; #pragma unroll
;             for (int e8 = 0; e8 < 8; ++e8) acc[e8] = __builtin_amdgcn_mfma_f32_16x16x32_bf16(*(const bf16x8*)(Vl + (16 * e8 + fr) * LP + ((32 * s + 8 * fq) ^ ((e8 & 3) << 4))), pf[s], acc[e8], 0, 0, 0);
; #pragma unroll
;         for (int dir = 0; dir < 2; ++dir) {
;             const unsigned char* sl = lds + ST_OFF + dir * 32768 + fr * 256;
;             const float sc = dir == 0 ? __builtin_amdgcn_exp2f(lgf2 * (float)(cq + 1)) : __builtin_amdgcn_exp2f(lgb2 * (float)(128 - cq));
; #pragma unroll
;             for (int e8 = 0; e8 < 8; ++e8) {
;                 f32x4 a2 = (f32x4){0.f, 0.f, 0.f, 0.f};
; #pragma unroll
;                 for (int ks = 0; ks < 4; ++ks) a2 = __builtin_amdgcn_mfma_f32_16x16x32_bf16(*(const bf16x8*)(sl + e8 * 4096 + (((4 * ks + fq) ^ fr) << 4)), qf[ks], a2, 0, 0, 0);
;                 acc[e8] += a2 * sc;
;             }
;         }
	v_mfma_f32_16x16x32_bf16 v[20:23], v[220:223], v[48:51], v[28:31]
	ds_read_b128 v[220:223], v89 offset:61120
	s_nop 2
	s_waitcnt lgkmcnt(5)
	v_mfma_f32_16x16x32_bf16 v[94:97], v[224:227], v[48:51], v[32:35]
	ds_read_b128 v[224:227], v88 offset:65472
	s_nop 1
	s_waitcnt lgkmcnt(5)
	v_mfma_f32_16x16x32_bf16 v[28:31], v[228:231], v[48:51], v[36:39]
	s_nop 2
	s_waitcnt lgkmcnt(4)
	v_mfma_f32_16x16x32_bf16 v[32:35], v[232:235], v[48:51], v[40:43]
	s_nop 2
	s_waitcnt lgkmcnt(3)
	v_mfma_f32_16x16x32_bf16 v[36:39], v[236:239], v[48:51], v[44:47]
	s_nop 2
	s_waitcnt lgkmcnt(2)
	v_mfma_f32_16x16x32_bf16 v[40:43], v[240:243], v[48:51], v[54:57]
	s_nop 2
	s_waitcnt lgkmcnt(1)
	v_mfma_f32_16x16x32_bf16 v[44:47], v[220:223], v[48:51], v[90:93]
	s_nop 2
	v_lshl_add_u32 v90, v53, 1, v52
	ds_read_b128 v[228:231], v90 offset:43520
	ds_read_b128 v[232:235], v89 offset:35008
	ds_read_b128 v[236:239], v88 offset:39360
	ds_read_b128 v[240:243], v88 offset:48000
	ds_read_b128 v[220:223], v89 offset:52416
	s_waitcnt lgkmcnt(5)
	v_mfma_f32_16x16x32_bf16 v[48:51], v[224:227], v[48:51], v[16:19]
	ds_read_b128 v[224:227], v88 offset:56768
	s_nop 1
	s_waitcnt lgkmcnt(4)
	v_mfma_f32_16x16x32_bf16 v[20:23], v[232:235], v[24:27], v[20:23]
	ds_read_b128 v[232:235], v90 offset:60928
	v_mfma_f32_16x16x32_bf16 v[56:59], v[228:231], v[24:27], v[28:31]
	ds_read_b128 v[228:231], v88 offset:65408
	s_nop 2
	s_waitcnt lgkmcnt(4)
	v_mfma_f32_16x16x32_bf16 v[52:55], v[240:243], v[24:27], v[32:35]
	s_waitcnt lgkmcnt(3)
	v_mfma_f32_16x16x32_bf16 v[36:39], v[220:223], v[24:27], v[36:39]
	s_waitcnt lgkmcnt(2)
	v_mfma_f32_16x16x32_bf16 v[32:35], v[224:227], v[24:27], v[40:43]
	s_nop 1
	v_mfma_f32_16x16x32_bf16 v[16:19], v[236:239], v[24:27], v[94:97]
	s_waitcnt lgkmcnt(1)
	v_mfma_f32_16x16x32_bf16 v[28:31], v[232:235], v[24:27], v[44:47]
	s_waitcnt lgkmcnt(0)
	v_mfma_f32_16x16x32_bf16 v[24:27], v[228:231], v[24:27], v[48:51]
	v_lshl_add_u32 v41, v83, 8, s55
	v_sub_u32_e32 v40, 0x80, v86
	v_bitop3_b32 v43, v85, v83, 3 bitop3:0x6c
	v_cvt_f32_i32_e32 v40, v40
	v_lshl_add_u32 v43, v43, 4, v41
	ds_read_b128 v[240:243], v43
	v_bitop3_b32 v48, v84, v83, 4 bitop3:0x36
	v_mul_f32_e64 v40, -v63, v40
	v_lshl_add_u32 v63, v48, 4, v41
	ds_read_b128 v[220:223], v63
	s_waitcnt lgkmcnt(1)
	v_mfma_f32_16x16x32_bf16 v[44:47], v[240:243], v[4:7], 0
	v_exp_f32_e32 v42, v40
	v_add_u32_e32 v40, 1, v86
	v_cvt_f32_i32_e32 v40, v40
	s_waitcnt lgkmcnt(0)
	v_mfma_f32_16x16x32_bf16 v[44:47], v[220:223], v[12:15], v[44:47]
	v_bitop3_b32 v48, v84, v83, 8 bitop3:0x36
	v_lshl_add_u32 v100, v48, 4, v41
	ds_read_b128 v[224:227], v100
	s_waitcnt lgkmcnt(0)
	v_mfma_f32_16x16x32_bf16 v[44:47], v[224:227], v[0:3], v[44:47]
	v_bitop3_b32 v48, v84, v83, 12 bitop3:0x36
	v_lshl_add_u32 v83, v48, 4, v41
	ds_read_b128 v[236:239], v83
	ds_read_b128 v[232:235], v43 offset:4096
	ds_read_b128 v[228:231], v63 offset:4096
	ds_read_b128 v[240:243], v100 offset:4096
	ds_read_b128 v[220:223], v83 offset:4096
	ds_read_b128 v[224:227], v43 offset:8192
	v_mul_f32_e32 v40, v87, v40
	v_exp_f32_e32 v40, v40
	s_waitcnt lgkmcnt(5)
	v_mfma_f32_16x16x32_bf16 v[44:47], v[236:239], v[8:11], v[44:47]
	ds_read_b128 v[236:239], v63 offset:8192
	s_nop 7
	v_pk_fma_f32 v[48:49], v[40:41], v[46:47], v[22:23] op_sel_hi:[0,1,1]
	v_pk_fma_f32 v[50:51], v[40:41], v[44:45], v[20:21] op_sel_hi:[0,1,1]
	s_waitcnt lgkmcnt(5)
	v_mfma_f32_16x16x32_bf16 v[20:23], v[232:235], v[4:7], 0
	ds_read_b128 v[232:235], v100 offset:8192
	s_waitcnt lgkmcnt(5)
	v_mfma_f32_16x16x32_bf16 v[20:23], v[228:231], v[12:15], v[20:23]
	ds_read_b128 v[228:231], v83 offset:8192
	s_waitcnt lgkmcnt(5)
	v_mfma_f32_16x16x32_bf16 v[20:23], v[240:243], v[0:3], v[20:23]
	ds_read_b128 v[240:243], v63 offset:12288
	s_waitcnt lgkmcnt(5)
	v_mfma_f32_16x16x32_bf16 v[20:23], v[220:223], v[8:11], v[20:23]
	ds_read_b128 v[220:223], v43 offset:12288
	s_nop 7
	v_pk_fma_f32 v[44:45], v[40:41], v[22:23], v[18:19] op_sel_hi:[0,1,1]
	v_pk_fma_f32 v[46:47], v[40:41], v[20:21], v[16:17] op_sel_hi:[0,1,1]
	s_waitcnt lgkmcnt(5)
	v_mfma_f32_16x16x32_bf16 v[16:19], v[224:227], v[4:7], 0
	ds_read_b128 v[224:227], v100 offset:12288
	s_waitcnt lgkmcnt(5)
	v_mfma_f32_16x16x32_bf16 v[16:19], v[236:239], v[12:15], v[16:19]
	ds_read_b128 v[236:239], v83 offset:12288
	s_waitcnt lgkmcnt(5)
	v_mfma_f32_16x16x32_bf16 v[16:19], v[232:235], v[0:3], v[16:19]
	ds_read_b128 v[232:235], v63 offset:16384
	s_waitcnt lgkmcnt(5)
	v_mfma_f32_16x16x32_bf16 v[16:19], v[228:231], v[8:11], v[16:19]
	ds_read_b128 v[228:231], v43 offset:16384
	s_nop 6
	v_pk_fma_f32 v[58:59], v[40:41], v[18:19], v[58:59] op_sel_hi:[0,1,1]
	v_pk_fma_f32 v[56:57], v[40:41], v[16:17], v[56:57] op_sel_hi:[0,1,1]
	s_waitcnt lgkmcnt(4)
	v_mfma_f32_16x16x32_bf16 v[16:19], v[220:223], v[4:7], 0
	ds_read_b128 v[220:223], v100 offset:16384
	v_mfma_f32_16x16x32_bf16 v[16:19], v[240:243], v[12:15], v[16:19]
	ds_read_b128 v[240:243], v83 offset:16384
	s_waitcnt lgkmcnt(5)
	v_mfma_f32_16x16x32_bf16 v[16:19], v[224:227], v[0:3], v[16:19]
	ds_read_b128 v[224:227], v63 offset:20480
	s_waitcnt lgkmcnt(5)
	v_mfma_f32_16x16x32_bf16 v[16:19], v[236:239], v[8:11], v[16:19]
	ds_read_b128 v[236:239], v43 offset:20480
	s_nop 6
	v_pk_fma_f32 v[54:55], v[40:41], v[18:19], v[54:55] op_sel_hi:[0,1,1]
	v_pk_fma_f32 v[52:53], v[40:41], v[16:17], v[52:53] op_sel_hi:[0,1,1]
	s_waitcnt lgkmcnt(4)
	v_mfma_f32_16x16x32_bf16 v[16:19], v[228:231], v[4:7], 0
	ds_read_b128 v[228:231], v100 offset:20480
	v_mfma_f32_16x16x32_bf16 v[16:19], v[232:235], v[12:15], v[16:19]
	ds_read_b128 v[232:235], v83 offset:20480
	s_waitcnt lgkmcnt(5)
; __device__ __forceinline__ void ret_out(const bf16_t* proj, const float* cosT, const float* sinT, const float* decay, const float* gn_g, const float* gn_b,
;                         const bf16_t* states, bf16_t* mix, unsigned char* lds, int tid, int bx) {
;     ...
; #pragma unroll
;         for (int dir = 0; dir < 2; ++dir) {
;             const unsigned char* sl = lds + ST_OFF + dir * 32768 + fr * 256;
;             const float sc = dir == 0 ? __builtin_amdgcn_exp2f(lgf2 * (float)(cq + 1)) : __builtin_amdgcn_exp2f(lgb2 * (float)(128 - cq));
; #pragma unroll
;             for (int e8 = 0; e8 < 8; ++e8) {
;                 f32x4 a2 = (f32x4){0.f, 0.f, 0.f, 0.f};
; #pragma unroll
;                 for (int ks = 0; ks < 4; ++ks) a2 = __builtin_amdgcn_mfma_f32_16x16x32_bf16(*(const bf16x8*)(sl + e8 * 4096 + (((4 * ks + fq) ^ fr) << 4)), qf[ks], a2, 0, 0, 0);
;                 acc[e8] += a2 * sc;
;             }
;         }
	v_mfma_f32_16x16x32_bf16 v[16:19], v[220:223], v[0:3], v[16:19]
	ds_read_b128 v[220:223], v63 offset:24576
	s_waitcnt lgkmcnt(5)
	v_mfma_f32_16x16x32_bf16 v[16:19], v[240:243], v[8:11], v[16:19]
	ds_read_b128 v[240:243], v43 offset:24576
	s_nop 6
	v_pk_fma_f32 v[84:85], v[40:41], v[18:19], v[38:39] op_sel_hi:[0,1,1]
	v_pk_fma_f32 v[86:87], v[40:41], v[16:17], v[36:37] op_sel_hi:[0,1,1]
	s_waitcnt lgkmcnt(4)
	v_mfma_f32_16x16x32_bf16 v[16:19], v[236:239], v[4:7], 0
	ds_read_b128 v[236:239], v100 offset:24576
	v_mfma_f32_16x16x32_bf16 v[16:19], v[224:227], v[12:15], v[16:19]
	ds_read_b128 v[224:227], v83 offset:24576
	s_waitcnt lgkmcnt(5)
	v_mfma_f32_16x16x32_bf16 v[16:19], v[228:231], v[0:3], v[16:19]
	ds_read_b128 v[228:231], v63 offset:28672
	s_waitcnt lgkmcnt(5)
	v_mfma_f32_16x16x32_bf16 v[16:19], v[232:235], v[8:11], v[16:19]
	ds_read_b128 v[232:235], v43 offset:28672
	s_nop 6
	v_pk_fma_f32 v[88:89], v[40:41], v[18:19], v[34:35] op_sel_hi:[0,1,1]
	v_pk_fma_f32 v[90:91], v[40:41], v[16:17], v[32:33] op_sel_hi:[0,1,1]
	s_waitcnt lgkmcnt(4)
	v_mfma_f32_16x16x32_bf16 v[16:19], v[240:243], v[4:7], 0
	ds_read_b128 v[240:243], v100 offset:28672
	v_mfma_f32_16x16x32_bf16 v[16:19], v[220:223], v[12:15], v[16:19]
	ds_read_b128 v[220:223], v83 offset:28672
	s_waitcnt lgkmcnt(5)
	v_mfma_f32_16x16x32_bf16 v[16:19], v[236:239], v[0:3], v[16:19]
	ds_read_b128 v[236:239], v63 offset:32768
	s_waitcnt lgkmcnt(5)
	v_mfma_f32_16x16x32_bf16 v[16:19], v[224:227], v[8:11], v[16:19]
	ds_read_b128 v[224:227], v43 offset:32768
	s_nop 6
	v_pk_fma_f32 v[92:93], v[40:41], v[18:19], v[30:31] op_sel_hi:[0,1,1]
	v_pk_fma_f32 v[94:95], v[40:41], v[16:17], v[28:29] op_sel_hi:[0,1,1]
	s_waitcnt lgkmcnt(4)
	v_mfma_f32_16x16x32_bf16 v[16:19], v[232:235], v[4:7], 0
	ds_read_b128 v[232:235], v100 offset:32768
	v_mfma_f32_16x16x32_bf16 v[16:19], v[228:231], v[12:15], v[16:19]
	ds_read_b128 v[228:231], v83 offset:32768
	s_waitcnt lgkmcnt(5)
	v_mfma_f32_16x16x32_bf16 v[16:19], v[240:243], v[0:3], v[16:19]
	ds_read_b128 v[240:243], v63 offset:36864
	s_waitcnt lgkmcnt(5)
	v_mfma_f32_16x16x32_bf16 v[16:19], v[220:223], v[8:11], v[16:19]
	ds_read_b128 v[220:223], v43 offset:36864
	s_nop 6
	v_pk_fma_f32 v[96:97], v[40:41], v[18:19], v[26:27] op_sel_hi:[0,1,1]
	v_pk_fma_f32 v[98:99], v[40:41], v[16:17], v[24:25] op_sel_hi:[0,1,1]
	s_waitcnt lgkmcnt(4)
	v_mfma_f32_16x16x32_bf16 v[16:19], v[224:227], v[4:7], 0
	ds_read_b128 v[224:227], v100 offset:36864
	v_mfma_f32_16x16x32_bf16 v[16:19], v[236:239], v[12:15], v[16:19]
	ds_read_b128 v[236:239], v83 offset:36864
	s_waitcnt lgkmcnt(5)
	v_mfma_f32_16x16x32_bf16 v[16:19], v[232:235], v[0:3], v[16:19]
	ds_read_b128 v[232:235], v63 offset:57344
	s_waitcnt lgkmcnt(5)
	v_mfma_f32_16x16x32_bf16 v[16:19], v[228:231], v[8:11], v[16:19]
	ds_read_b128 v[228:231], v63 offset:40960
	s_nop 6
	v_pk_fma_f32 v[40:41], v[42:43], v[18:19], v[48:49] op_sel_hi:[0,1,1]
	v_pk_fma_f32 v[38:39], v[42:43], v[16:17], v[50:51] op_sel_hi:[0,1,1]
	s_waitcnt lgkmcnt(4)
	v_mfma_f32_16x16x32_bf16 v[16:19], v[220:223], v[4:7], 0
	ds_read_b128 v[220:223], v43 offset:40960
	v_mfma_f32_16x16x32_bf16 v[16:19], v[240:243], v[12:15], v[16:19]
	ds_read_b128 v[240:243], v100 offset:40960
	s_waitcnt lgkmcnt(5)
	v_mfma_f32_16x16x32_bf16 v[16:19], v[224:227], v[0:3], v[16:19]
	ds_read_b128 v[224:227], v83 offset:40960
	s_waitcnt lgkmcnt(5)
	v_mfma_f32_16x16x32_bf16 v[16:19], v[236:239], v[8:11], v[16:19]
	ds_read_b128 v[236:239], v63 offset:53248
	s_nop 6
	v_pk_fma_f32 v[36:37], v[42:43], v[18:19], v[44:45] op_sel_hi:[0,1,1]
	v_pk_fma_f32 v[34:35], v[42:43], v[16:17], v[46:47] op_sel_hi:[0,1,1]
	s_waitcnt lgkmcnt(3)
	v_mfma_f32_16x16x32_bf16 v[16:19], v[220:223], v[4:7], 0
	ds_read_b128 v[220:223], v63 offset:45056
	v_mfma_f32_16x16x32_bf16 v[16:19], v[228:231], v[12:15], v[16:19]
	ds_read_b128 v[228:231], v43 offset:45056
	s_waitcnt lgkmcnt(4)
	v_mfma_f32_16x16x32_bf16 v[16:19], v[240:243], v[0:3], v[16:19]
	ds_read_b128 v[240:243], v100 offset:45056
	s_waitcnt lgkmcnt(4)
	v_mfma_f32_16x16x32_bf16 v[16:19], v[224:227], v[8:11], v[16:19]
	ds_read_b128 v[224:227], v83 offset:45056
	s_nop 6
	v_pk_fma_f32 v[32:33], v[42:43], v[18:19], v[58:59] op_sel_hi:[0,1,1]
	v_pk_fma_f32 v[30:31], v[42:43], v[16:17], v[56:57] op_sel_hi:[0,1,1]
	s_waitcnt lgkmcnt(2)
	v_mfma_f32_16x16x32_bf16 v[16:19], v[228:231], v[4:7], 0
	ds_read_b128 v[228:231], v63 offset:49152
	v_lshlrev_b32_e32 v56, 16, v75
	v_and_b32_e32 v57, 0xffff0000, v75
	v_and_b32_e32 v75, 0xffff0000, v73
	v_mfma_f32_16x16x32_bf16 v[16:19], v[220:223], v[12:15], v[16:19]
	ds_read_b128 v[220:223], v43 offset:49152
	s_waitcnt lgkmcnt(3)
	v_mfma_f32_16x16x32_bf16 v[16:19], v[240:243], v[0:3], v[16:19]
	ds_read_b128 v[240:243], v100 offset:49152
	s_waitcnt lgkmcnt(3)
	v_mfma_f32_16x16x32_bf16 v[16:19], v[224:227], v[8:11], v[16:19]
	ds_read_b128 v[224:227], v83 offset:49152
	s_nop 6
	v_pk_fma_f32 v[28:29], v[42:43], v[18:19], v[54:55] op_sel_hi:[0,1,1]
	v_pk_fma_f32 v[26:27], v[42:43], v[16:17], v[52:53] op_sel_hi:[0,1,1]
	s_waitcnt lgkmcnt(2)
	v_mfma_f32_16x16x32_bf16 v[16:19], v[220:223], v[4:7], 0
	ds_read_b128 v[220:223], v43 offset:53248
	v_lshlrev_b32_e32 v52, 16, v77
	v_and_b32_e32 v53, 0xffff0000, v77
	v_mfma_f32_16x16x32_bf16 v[16:19], v[228:231], v[12:15], v[16:19]
	ds_read_b128 v[228:231], v100 offset:53248
	s_waitcnt lgkmcnt(3)
	v_mfma_f32_16x16x32_bf16 v[16:19], v[240:243], v[0:3], v[16:19]
	ds_read_b128 v[240:243], v83 offset:53248
	s_waitcnt lgkmcnt(3)
	v_mfma_f32_16x16x32_bf16 v[16:19], v[224:227], v[8:11], v[16:19]
	ds_read_b128 v[224:227], v43 offset:57344
	s_nop 7
	v_pk_fma_f32 v[24:25], v[42:43], v[18:19], v[84:85] op_sel_hi:[0,1,1]
	v_pk_fma_f32 v[22:23], v[42:43], v[16:17], v[86:87] op_sel_hi:[0,1,1]
	s_waitcnt lgkmcnt(3)
; __device__ __forceinline__ float bf_lo(unsigned u) { return __uint_as_float(u << 16); }
; __device__ __forceinline__ float bf_hi(unsigned u) { return __uint_as_float(u & 0xffff0000u); }
; __device__ __forceinline__ float silu_f(float x) { return x * __builtin_amdgcn_rcpf(1.0f + __expf(-x)); }
; __device__ __forceinline__ void ret_out(const bf16_t* proj, const float* cosT, const float* sinT, const float* decay, const float* gn_g, const float* gn_b,
;                         const bf16_t* states, bf16_t* mix, unsigned char* lds, int tid, int bx) {
;     ...
;             for (int e8 = 0; e8 < 8; ++e8) {
;                 f32x4 a2 = (f32x4){0.f, 0.f, 0.f, 0.f};
; #pragma unroll
;                 for (int ks = 0; ks < 4; ++ks) a2 = __builtin_amdgcn_mfma_f32_16x16x32_bf16(*(const bf16x8*)(sl + e8 * 4096 + (((4 * ks + fq) ^ fr) << 4)), qf[ks], a2, 0, 0, 0);
;                 acc[e8] += a2 * sc;
;             }
;         }
;         float sm = 0.f;
; #pragma unroll
;         for (int e8 = 0; e8 < 8; ++e8) sm += (acc[e8][0] + acc[e8][1]) + (acc[e8][2] + acc[e8][3]);
;         sm += __shfl_xor(sm, 16); sm += __shfl_xor(sm, 32);
;         const float mu = sm * (1.0f / 128.0f);
;         float vs = 0.f;
; #pragma unroll
;         for (int e8 = 0; e8 < 8; ++e8)
; #pragma unroll
;             for (int r = 0; r < 4; ++r) { const float dlt = acc[e8][r] - mu; vs += dlt * dlt; }
;         vs += __shfl_xor(vs, 16); vs += __shfl_xor(vs, 32);
;         const float rstd = 1.0f / sqrtf(vs * (1.0f / 128.0f) + 1e-5f);
;         bf16_t* op = mix + (size_t)(b * SEQ + tq) * 1024 + h * 128 + 4 * fq;
; #pragma unroll
;         for (int e8 = 0; e8 < 8; ++e8) {
;             const u32x2 gw = gwv[e8];
;             const float4 gg = *(const float4*)(gnl + h * 128 + 16 * e8 + 4 * fq), gb = *(const float4*)(gnl + 768 + h * 128 + 16 * e8 + 4 * fq);
;             const float y0 = ((acc[e8][0] - mu) * rstd * gg.x + gb.x) * silu_f(bf_lo(gw.x));
;             const float y1 = ((acc[e8][1] - mu) * rstd * gg.y + gb.y) * silu_f(bf_hi(gw.x));
;             const float y2 = ((acc[e8][2] - mu) * rstd * gg.z + gb.z) * silu_f(bf_lo(gw.y));
;             const float y3 = ((acc[e8][3] - mu) * rstd * gg.w + gb.w) * silu_f(bf_hi(gw.y));
	v_mfma_f32_16x16x32_bf16 v[16:19], v[220:223], v[4:7], 0
	ds_read_b128 v[220:223], v100 offset:57344
	v_mfma_f32_16x16x32_bf16 v[16:19], v[236:239], v[12:15], v[16:19]
	ds_read_b128 v[236:239], v83 offset:57344
	s_waitcnt lgkmcnt(4)
	v_mfma_f32_16x16x32_bf16 v[16:19], v[228:231], v[0:3], v[16:19]
	ds_read_b128 v[228:231], v43 offset:61440
	s_waitcnt lgkmcnt(4)
	v_mfma_f32_16x16x32_bf16 v[16:19], v[240:243], v[8:11], v[16:19]
	ds_read_b128 v[240:243], v63 offset:61440
	s_nop 6
	v_pk_fma_f32 v[20:21], v[42:43], v[18:19], v[88:89] op_sel_hi:[0,1,1]
	s_waitcnt lgkmcnt(4)
	v_mfma_f32_16x16x32_bf16 v[44:47], v[224:227], v[4:7], 0
	ds_read_b128 v[224:227], v100 offset:61440
	v_fma_f32 v18, v42, v16, v90
	v_fma_f32 v19, v42, v17, v91
	v_mfma_f32_16x16x32_bf16 v[44:47], v[232:235], v[12:15], v[44:47]
	ds_read_b128 v[232:235], v83 offset:61440
	s_waitcnt lgkmcnt(5)
	v_mfma_f32_16x16x32_bf16 v[44:47], v[220:223], v[0:3], v[44:47]
	s_waitcnt lgkmcnt(4)
	v_mfma_f32_16x16x32_bf16 v[44:47], v[236:239], v[8:11], v[44:47]
	s_nop 7
	v_pk_fma_f32 v[48:49], v[42:43], v[46:47], v[92:93] op_sel_hi:[0,1,1]
	v_pk_fma_f32 v[16:17], v[42:43], v[44:45], v[94:95] op_sel_hi:[0,1,1]
	s_waitcnt lgkmcnt(3)
	v_mfma_f32_16x16x32_bf16 v[4:7], v[228:231], v[4:7], 0
	s_waitcnt lgkmcnt(2)
	v_mfma_f32_16x16x32_bf16 v[4:7], v[240:243], v[12:15], v[4:7]
	s_waitcnt lgkmcnt(1)
	v_mfma_f32_16x16x32_bf16 v[0:3], v[224:227], v[0:3], v[4:7]
	s_nop 4
	s_waitcnt lgkmcnt(0)
	v_mfma_f32_16x16x32_bf16 v[0:3], v[232:235], v[8:11], v[0:3]
	v_mov_b32_e32 v4, v38
	v_mov_b32_e32 v5, v34
	v_mov_b32_e32 v6, v39
	v_mov_b32_e32 v7, v35
	v_pk_add_f32 v[4:5], v[4:5], v[6:7]
	v_mov_b32_e32 v6, v40
	v_mov_b32_e32 v7, v36
	v_mov_b32_e32 v8, v41
	v_mov_b32_e32 v9, v37
	v_pk_add_f32 v[6:7], v[6:7], v[8:9]
	v_mov_b32_e32 v8, v30
	v_pk_add_f32 v[4:5], v[4:5], v[6:7]
	v_pk_mov_b32 v[6:7], v[30:31], v[32:33] op_sel:[1,0]
	v_mov_b32_e32 v9, v33
	v_pk_add_f32 v[6:7], v[6:7], v[8:9]
	v_add_f32_e32 v4, 0, v4
	v_pk_add_f32 v[6:7], v[6:7], v[6:7] op_sel:[0,1] op_sel_hi:[1,0]
	v_add_f32_e32 v4, v4, v5
	v_add_f32_e32 v8, v26, v27
	v_add_f32_e32 v10, v28, v29
	v_mov_b32_e32 v5, v22
	v_mov_b32_e32 v7, v23
	v_mov_b32_e32 v9, v24
	v_mov_b32_e32 v11, v25
	v_pk_add_f32 v[4:5], v[4:5], v[6:7]
	v_pk_add_f32 v[6:7], v[8:9], v[10:11]
	v_mov_b32_e32 v8, v18
	v_pk_add_f32 v[4:5], v[4:5], v[6:7]
	v_pk_mov_b32 v[6:7], v[18:19], v[20:21] op_sel:[1,0]
	v_mov_b32_e32 v9, v21
	v_pk_add_f32 v[6:7], v[6:7], v[8:9]
	v_pk_fma_f32 v[2:3], v[42:43], v[2:3], v[96:97] op_sel_hi:[0,1,1]
	v_pk_fma_f32 v[0:1], v[42:43], v[0:1], v[98:99] op_sel_hi:[0,1,1]
	v_pk_add_f32 v[4:5], v[4:5], v[4:5] op_sel:[0,1] op_sel_hi:[1,0]
	v_pk_add_f32 v[6:7], v[6:7], v[6:7] op_sel:[0,1] op_sel_hi:[1,0]
	v_add_f32_e32 v8, v16, v17
	v_add_f32_e32 v10, v48, v49
	v_mov_b32_e32 v5, v0
	v_mov_b32_e32 v7, v1
	v_mov_b32_e32 v9, v2
	v_mov_b32_e32 v11, v3
	v_pk_add_f32 v[4:5], v[4:5], v[6:7]
	v_pk_add_f32 v[6:7], v[8:9], v[10:11]
	s_nop 0
	v_pk_add_f32 v[4:5], v[4:5], v[6:7]
	s_nop 0
	v_add_f32_e32 v4, v4, v5
	ds_bpermute_b32 v5, v61, v4
	s_waitcnt lgkmcnt(0)
	v_add_f32_e32 v4, v4, v5
	ds_bpermute_b32 v5, v82, v4
	s_waitcnt lgkmcnt(0)
	v_add_f32_e32 v4, v4, v5
	v_mul_f32_e32 v14, 0x3c000000, v4
	v_pk_add_f32 v[6:7], v[48:49], v[14:15] op_sel_hi:[1,0] neg_lo:[0,1] neg_hi:[0,1]
	v_pk_add_f32 v[4:5], v[0:1], v[14:15] op_sel_hi:[1,0] neg_lo:[0,1] neg_hi:[0,1]
	v_pk_add_f32 v[2:3], v[2:3], v[14:15] op_sel_hi:[1,0] neg_lo:[0,1] neg_hi:[0,1]
	v_add_u32_e32 v15, s0, v62
	v_lshlrev_b32_e32 v48, 16, v79
	v_add_u32_e32 v83, 0x21000, v15
	v_add_u32_e32 v148, 0x21c00, v15
	v_pk_add_f32 v[62:63], v[40:41], v[14:15] op_sel_hi:[1,0] neg_lo:[0,1] neg_hi:[0,1]
	v_mul_f32_e32 v15, 0xbfb8aa3b, v48
	v_exp_f32_e32 v15, v15
	v_and_b32_e32 v49, 0xffff0000, v79
	v_lshlrev_b64 v[0:1], 11, v[80:81]
	v_pk_mul_f32 v[80:81], v[62:63], v[62:63]
	v_add_f32_e32 v15, 1.0, v15
	v_rcp_f32_e32 v50, v15
	v_mul_f32_e32 v15, 0xbfb8aa3b, v49
	v_exp_f32_e32 v15, v15
	v_pk_mul_f32 v[8:9], v[6:7], v[6:7]
	v_pk_mul_f32 v[10:11], v[4:5], v[4:5]
	v_pk_mul_f32 v[12:13], v[2:3], v[2:3]
	v_add_f32_e32 v15, 1.0, v15
	v_pk_add_f32 v[86:87], v[38:39], v[14:15] op_sel_hi:[1,0] neg_lo:[0,1] neg_hi:[0,1]
	v_lshlrev_b32_e32 v38, 16, v78
	v_rcp_f32_e32 v51, v15
	v_mul_f32_e32 v15, 0xbfb8aa3b, v38
	v_exp_f32_e32 v15, v15
	v_and_b32_e32 v39, 0xffff0000, v78
	v_pk_mul_f32 v[84:85], v[50:51], v[48:49]
	v_pk_mul_f32 v[88:89], v[86:87], v[86:87]
	v_add_f32_e32 v15, 1.0, v15
	v_rcp_f32_e32 v48, v15
	v_mul_f32_e32 v15, 0xbfb8aa3b, v39
	v_exp_f32_e32 v15, v15
	v_add_f32_e32 v88, v88, v89
	v_add_f32_e32 v80, v80, v88
	v_add_f32_e32 v80, v81, v80
	v_add_f32_e32 v15, 1.0, v15
	v_rcp_f32_e32 v49, v15
	v_pk_add_f32 v[92:93], v[36:37], v[14:15] op_sel_hi:[1,0] neg_lo:[0,1] neg_hi:[0,1]
	v_mul_f32_e32 v15, 0xbfb8aa3b, v52
	v_exp_f32_e32 v15, v15
	v_pk_mul_f32 v[94:95], v[92:93], v[92:93]
	ds_read_b128 v[40:43], v83
	ds_read_b128 v[44:47], v148
	v_pk_mul_f32 v[90:91], v[48:49], v[38:39]
	v_add_f32_e32 v15, 1.0, v15
	v_rcp_f32_e32 v54, v15
	v_mul_f32_e32 v15, 0xbfb8aa3b, v53
	v_exp_f32_e32 v15, v15
	ds_read_b128 v[36:39], v83 offset:64
	ds_read_b128 v[48:51], v148 offset:64
	v_lshl_add_u64 v[0:1], s[42:43], 0, v[0:1]
	v_lshl_add_u64 v[0:1], v[0:1], 0, s[46:47]
	v_add_f32_e32 v15, 1.0, v15
	v_pk_add_f32 v[98:99], v[34:35], v[14:15] op_sel_hi:[1,0] neg_lo:[0,1] neg_hi:[0,1]
	v_lshlrev_b32_e32 v34, 16, v76
	v_rcp_f32_e32 v55, v15
	v_mul_f32_e32 v15, 0xbfb8aa3b, v34
	v_exp_f32_e32 v15, v15
	v_and_b32_e32 v35, 0xffff0000, v76
	v_pk_mul_f32 v[96:97], v[54:55], v[52:53]
	v_pk_mul_f32 v[100:101], v[98:99], v[98:99]
	v_add_f32_e32 v15, 1.0, v15
; __device__ __forceinline__ float bf_lo(unsigned u) { return __uint_as_float(u << 16); }
; __device__ __forceinline__ float bf_hi(unsigned u) { return __uint_as_float(u & 0xffff0000u); }
; __device__ __forceinline__ float silu_f(float x) { return x * __builtin_amdgcn_rcpf(1.0f + __expf(-x)); }
; __device__ __forceinline__ void ret_out(const bf16_t* proj, const float* cosT, const float* sinT, const float* decay, const float* gn_g, const float* gn_b,
;                         const bf16_t* states, bf16_t* mix, unsigned char* lds, int tid, int bx) {
;     ...
;         float sm = 0.f;
; #pragma unroll
;         for (int e8 = 0; e8 < 8; ++e8) sm += (acc[e8][0] + acc[e8][1]) + (acc[e8][2] + acc[e8][3]);
;         sm += __shfl_xor(sm, 16); sm += __shfl_xor(sm, 32);
;         const float mu = sm * (1.0f / 128.0f);
;         float vs = 0.f;
; #pragma unroll
;         for (int e8 = 0; e8 < 8; ++e8)
; #pragma unroll
;             for (int r = 0; r < 4; ++r) { const float dlt = acc[e8][r] - mu; vs += dlt * dlt; }
;         vs += __shfl_xor(vs, 16); vs += __shfl_xor(vs, 32);
;         const float rstd = 1.0f / sqrtf(vs * (1.0f / 128.0f) + 1e-5f);
;         bf16_t* op = mix + (size_t)(b * SEQ + tq) * 1024 + h * 128 + 4 * fq;
; #pragma unroll
;         for (int e8 = 0; e8 < 8; ++e8) {
;             const u32x2 gw = gwv[e8];
;             const float4 gg = *(const float4*)(gnl + h * 128 + 16 * e8 + 4 * fq), gb = *(const float4*)(gnl + 768 + h * 128 + 16 * e8 + 4 * fq);
;             const float y0 = ((acc[e8][0] - mu) * rstd * gg.x + gb.x) * silu_f(bf_lo(gw.x));
;             const float y1 = ((acc[e8][1] - mu) * rstd * gg.y + gb.y) * silu_f(bf_hi(gw.x));
;             const float y2 = ((acc[e8][2] - mu) * rstd * gg.z + gb.z) * silu_f(bf_lo(gw.y));
;             const float y3 = ((acc[e8][3] - mu) * rstd * gg.w + gb.w) * silu_f(bf_hi(gw.y));
	v_rcp_f32_e32 v52, v15
	v_mul_f32_e32 v15, 0xbfb8aa3b, v35
	v_exp_f32_e32 v15, v15
	v_add_f32_e32 v80, v100, v80
	v_add_f32_e32 v80, v101, v80
	v_add_f32_e32 v80, v94, v80
	v_add_f32_e32 v15, 1.0, v15
	v_rcp_f32_e32 v53, v15
	v_pk_add_f32 v[104:105], v[32:33], v[14:15] op_sel_hi:[1,0] neg_lo:[0,1] neg_hi:[0,1]
	v_mul_f32_e32 v15, 0xbfb8aa3b, v56
	v_exp_f32_e32 v15, v15
	v_add_f32_e32 v80, v95, v80
	v_pk_mul_f32 v[106:107], v[104:105], v[104:105]
	v_lshl_add_u64 v[0:1], v[0:1], 0, v[154:155]
	v_add_f32_e32 v15, 1.0, v15
	v_rcp_f32_e32 v58, v15
	v_mul_f32_e32 v15, 0xbfb8aa3b, v57
	v_exp_f32_e32 v15, v15
	v_pk_mul_f32 v[102:103], v[52:53], v[34:35]
	ds_read_b128 v[32:35], v83 offset:128
	ds_read_b128 v[52:55], v148 offset:128
	v_add_f32_e32 v15, 1.0, v15
	v_pk_add_f32 v[110:111], v[30:31], v[14:15] op_sel_hi:[1,0] neg_lo:[0,1] neg_hi:[0,1]
	v_lshlrev_b32_e32 v30, 16, v74
	v_rcp_f32_e32 v59, v15
	v_mul_f32_e32 v15, 0xbfb8aa3b, v30
	v_exp_f32_e32 v15, v15
	v_and_b32_e32 v31, 0xffff0000, v74
	v_pk_mul_f32 v[108:109], v[58:59], v[56:57]
	v_lshlrev_b32_e32 v74, 16, v73
	v_add_f32_e32 v15, 1.0, v15
	v_rcp_f32_e32 v56, v15
	v_mul_f32_e32 v15, 0xbfb8aa3b, v31
	v_exp_f32_e32 v15, v15
	v_pk_mul_f32 v[112:113], v[110:111], v[110:111]
	v_add_f32_e32 v15, 1.0, v15
	v_rcp_f32_e32 v57, v15
	v_pk_add_f32 v[116:117], v[28:29], v[14:15] op_sel_hi:[1,0] neg_lo:[0,1] neg_hi:[0,1]
	v_mul_f32_e32 v15, 0xbfb8aa3b, v74
	v_exp_f32_e32 v15, v15
	v_add_f32_e32 v80, v112, v80
	v_add_f32_e32 v80, v113, v80
	v_add_f32_e32 v80, v106, v80
	v_add_f32_e32 v15, 1.0, v15
	v_rcp_f32_e32 v76, v15
	v_mul_f32_e32 v15, 0xbfb8aa3b, v75
	v_exp_f32_e32 v15, v15
	v_add_f32_e32 v80, v107, v80
	v_pk_mul_f32 v[118:119], v[116:117], v[116:117]
	v_pk_mul_f32 v[114:115], v[56:57], v[30:31]
	v_add_f32_e32 v15, 1.0, v15
	v_pk_add_f32 v[122:123], v[26:27], v[14:15] op_sel_hi:[1,0] neg_lo:[0,1] neg_hi:[0,1]
	v_lshlrev_b32_e32 v26, 16, v72
	v_rcp_f32_e32 v77, v15
	v_mul_f32_e32 v15, 0xbfb8aa3b, v26
	v_exp_f32_e32 v15, v15
	v_and_b32_e32 v27, 0xffff0000, v72
	v_pk_mul_f32 v[120:121], v[76:77], v[74:75]
	v_lshlrev_b32_e32 v76, 16, v71
	v_add_f32_e32 v15, 1.0, v15
	v_rcp_f32_e32 v72, v15
	v_mul_f32_e32 v15, 0xbfb8aa3b, v27
	v_exp_f32_e32 v15, v15
	v_and_b32_e32 v77, 0xffff0000, v71
	v_pk_mul_f32 v[124:125], v[122:123], v[122:123]
	ds_read_b128 v[28:31], v83 offset:192
	ds_read_b128 v[56:59], v148 offset:192
	v_add_f32_e32 v15, 1.0, v15
	v_rcp_f32_e32 v73, v15
	v_pk_add_f32 v[128:129], v[24:25], v[14:15] op_sel_hi:[1,0] neg_lo:[0,1] neg_hi:[0,1]
	v_mul_f32_e32 v15, 0xbfb8aa3b, v76
	v_exp_f32_e32 v15, v15
	v_add_f32_e32 v80, v124, v80
	v_add_f32_e32 v80, v125, v80
	v_add_f32_e32 v80, v118, v80
	v_add_f32_e32 v15, 1.0, v15
	v_rcp_f32_e32 v78, v15
	v_mul_f32_e32 v15, 0xbfb8aa3b, v77
	v_exp_f32_e32 v15, v15
	v_add_f32_e32 v80, v119, v80
	v_pk_mul_f32 v[130:131], v[128:129], v[128:129]
	v_pk_mul_f32 v[126:127], v[72:73], v[26:27]
	v_add_f32_e32 v15, 1.0, v15
	v_pk_add_f32 v[134:135], v[22:23], v[14:15] op_sel_hi:[1,0] neg_lo:[0,1] neg_hi:[0,1]
	v_lshlrev_b32_e32 v22, 16, v70
	v_rcp_f32_e32 v79, v15
	v_mul_f32_e32 v15, 0xbfb8aa3b, v22
	v_exp_f32_e32 v15, v15
	v_and_b32_e32 v23, 0xffff0000, v70
	v_pk_mul_f32 v[136:137], v[134:135], v[134:135]
	ds_read_b128 v[24:27], v83 offset:256
	ds_read_b128 v[72:75], v148 offset:256
	v_add_f32_e32 v15, 1.0, v15
	v_rcp_f32_e32 v70, v15
	v_mul_f32_e32 v15, 0xbfb8aa3b, v23
	v_exp_f32_e32 v15, v15
	v_add_f32_e32 v80, v136, v80
	v_add_f32_e32 v80, v137, v80
	v_add_f32_e32 v80, v130, v80
	v_add_f32_e32 v15, 1.0, v15
	v_rcp_f32_e32 v71, v15
	v_pk_add_f32 v[138:139], v[20:21], v[14:15] op_sel_hi:[1,0] neg_lo:[0,1] neg_hi:[0,1]
	v_mul_f32_e32 v15, 0xbfb8aa3b, v142
	v_exp_f32_e32 v15, v15
	v_add_f32_e32 v80, v131, v80
	v_pk_mul_f32 v[140:141], v[138:139], v[138:139]
	v_pk_mul_f32 v[132:133], v[78:79], v[76:77]
	v_add_f32_e32 v15, 1.0, v15
	v_rcp_f32_e32 v144, v15
	v_mul_f32_e32 v15, 0xbfb8aa3b, v143
	v_exp_f32_e32 v15, v15
	v_pk_mul_f32 v[70:71], v[70:71], v[22:23]
	ds_read_b128 v[20:23], v83 offset:320
	ds_read_b128 v[76:79], v148 offset:320
	v_add_f32_e32 v15, 1.0, v15
	v_rcp_f32_e32 v145, v15
	v_pk_add_f32 v[18:19], v[18:19], v[14:15] op_sel_hi:[1,0] neg_lo:[0,1] neg_hi:[0,1]
	v_mul_f32_e32 v15, 0xbfb8aa3b, v146
	v_exp_f32_e32 v15, v15
	v_pk_mul_f32 v[142:143], v[144:145], v[142:143]
	v_pk_mul_f32 v[144:145], v[18:19], v[18:19]
	v_add_f32_e32 v15, 1.0, v15
	v_rcp_f32_e32 v68, v15
	v_mul_f32_e32 v15, 0xbfb8aa3b, v147
	v_exp_f32_e32 v15, v15
	v_add_f32_e32 v80, v144, v80
	v_add_f32_e32 v80, v145, v80
	v_add_f32_e32 v80, v140, v80
	v_add_f32_e32 v15, 1.0, v15
	v_pk_add_f32 v[16:17], v[16:17], v[14:15] op_sel_hi:[1,0] neg_lo:[0,1] neg_hi:[0,1]
	v_rcp_f32_e32 v69, v15
	v_pk_mul_f32 v[14:15], v[16:17], v[16:17]
	v_add_f32_e32 v80, v141, v80
	v_add_f32_e32 v14, v14, v80
	v_add_f32_e32 v14, v15, v14
	v_add_f32_e32 v8, v8, v14
	v_add_f32_e32 v8, v9, v8
	v_add_f32_e32 v8, v10, v8
	v_add_f32_e32 v8, v11, v8
	v_add_f32_e32 v8, v12, v8
	v_add_f32_e32 v8, v13, v8
	ds_bpermute_b32 v9, v61, v8
	v_pk_mul_f32 v[68:69], v[68:69], v[146:147]
	s_waitcnt lgkmcnt(0)
	v_add_f32_e32 v8, v8, v9
	ds_bpermute_b32 v9, v82, v8
	s_waitcnt lgkmcnt(0)
; __device__ __forceinline__ float bf_lo(unsigned u) { return __uint_as_float(u << 16); }
; __device__ __forceinline__ float bf_hi(unsigned u) { return __uint_as_float(u & 0xffff0000u); }
; __device__ __forceinline__ float silu_f(float x) { return x * __builtin_amdgcn_rcpf(1.0f + __expf(-x)); }
; __device__ __forceinline__ void ret_out(const bf16_t* proj, const float* cosT, const float* sinT, const float* decay, const float* gn_g, const float* gn_b,
;                         const bf16_t* states, bf16_t* mix, unsigned char* lds, int tid, int bx) {
;     ...
;         const float mu = sm * (1.0f / 128.0f);
;         float vs = 0.f;
; #pragma unroll
;         for (int e8 = 0; e8 < 8; ++e8)
; #pragma unroll
;             for (int r = 0; r < 4; ++r) { const float dlt = acc[e8][r] - mu; vs += dlt * dlt; }
;         vs += __shfl_xor(vs, 16); vs += __shfl_xor(vs, 32);
;         const float rstd = 1.0f / sqrtf(vs * (1.0f / 128.0f) + 1e-5f);
;         bf16_t* op = mix + (size_t)(b * SEQ + tq) * 1024 + h * 128 + 4 * fq;
; #pragma unroll
;         for (int e8 = 0; e8 < 8; ++e8) {
;             const u32x2 gw = gwv[e8];
;             const float4 gg = *(const float4*)(gnl + h * 128 + 16 * e8 + 4 * fq), gb = *(const float4*)(gnl + 768 + h * 128 + 16 * e8 + 4 * fq);
;             const float y0 = ((acc[e8][0] - mu) * rstd * gg.x + gb.x) * silu_f(bf_lo(gw.x));
;             const float y1 = ((acc[e8][1] - mu) * rstd * gg.y + gb.y) * silu_f(bf_hi(gw.x));
;             const float y2 = ((acc[e8][2] - mu) * rstd * gg.z + gb.z) * silu_f(bf_lo(gw.y));
;             const float y3 = ((acc[e8][3] - mu) * rstd * gg.w + gb.w) * silu_f(bf_hi(gw.y));
;             u32x2 w; w.x = cvt_pk_bf16(y0, y1); w.y = cvt_pk_bf16(y2, y3);
;             *(u32x2*)(op + 16 * e8) = w;
;         }
	v_add_f32_e32 v8, v8, v9
	v_fmamk_f32 v8, v8, 0x3c000000, v175
	v_cmp_gt_f32_e32 vcc, s64, v8
	v_mul_f32_e32 v9, 0x4f800000, v8
	s_nop 0
	v_cndmask_b32_e32 v8, v8, v9, vcc
	v_sqrt_f32_e32 v9, v8
	s_nop 0
	v_add_u32_e32 v10, -1, v9
	v_fma_f32 v11, -v10, v9, v8
	v_cmp_ge_f32_e64 s[36:37], 0, v11
	v_add_u32_e32 v11, 1, v9
	s_nop 0
	v_cndmask_b32_e64 v10, v9, v10, s[36:37]
	v_fma_f32 v9, -v11, v9, v8
	v_cmp_lt_f32_e64 s[36:37], 0, v9
	s_nop 1
	v_cndmask_b32_e64 v9, v10, v11, s[36:37]
	v_mul_f32_e32 v10, 0x37800000, v9
	v_cndmask_b32_e32 v9, v9, v10, vcc
	v_cmp_class_f32_e32 vcc, v8, v176
	s_nop 1
	v_cndmask_b32_e32 v8, v9, v8, vcc
	v_div_scale_f32 v9, s[0:1], v8, v8, 1.0
	v_rcp_f32_e32 v10, v9
	s_nop 0
	v_fma_f32 v11, -v9, v10, 1.0
	v_fmac_f32_e32 v10, v11, v10
	v_div_scale_f32 v11, vcc, 1.0, v8, 1.0
	v_mul_f32_e32 v12, v11, v10
	v_fma_f32 v13, -v9, v12, v11
	v_fmac_f32_e32 v12, v13, v10
	v_fma_f32 v9, -v9, v12, v11
	v_div_fmas_f32 v9, v9, v10, v12
	v_div_fixup_f32 v80, v9, v8, 1.0
	v_bfe_u32 v88, v172, 4, 1
	v_mul_u32_u24_e32 v88, 24, v88
	s_nop 0
	v_add_co_u32_e32 v0, vcc, v0, v88
	s_nop 1
	v_addc_co_u32_e32 v1, vcc, 0, v1, vcc
	v_pk_mul_f32 v[8:9], v[86:87], v[80:81] op_sel_hi:[1,0]
	v_pk_mul_f32 v[10:11], v[62:63], v[80:81] op_sel_hi:[1,0]
	v_pk_fma_f32 v[8:9], v[40:41], v[8:9], v[44:45]
	v_pk_fma_f32 v[10:11], v[42:43], v[10:11], v[46:47]
	v_pk_mul_f32 v[8:9], v[90:91], v[8:9]
	v_pk_mul_f32 v[10:11], v[84:85], v[10:11]
	v_cvt_pk_bf16_f32 v8, v8, v9
	v_cvt_pk_bf16_f32 v9, v10, v11
	v_pk_mul_f32 v[40:41], v[98:99], v[80:81] op_sel_hi:[1,0]
	v_pk_mul_f32 v[42:43], v[92:93], v[80:81] op_sel_hi:[1,0]
	v_pk_fma_f32 v[40:41], v[36:37], v[40:41], v[48:49]
	v_pk_fma_f32 v[42:43], v[38:39], v[42:43], v[50:51]
	v_pk_mul_f32 v[40:41], v[102:103], v[40:41]
	v_pk_mul_f32 v[42:43], v[96:97], v[42:43]
	v_cvt_pk_bf16_f32 v10, v40, v41
	v_cvt_pk_bf16_f32 v11, v42, v43
	s_nop 1
	v_permlane16_swap_b32 v8, v10
	v_permlane16_swap_b32 v9, v11
	global_store_dwordx4 v[0:1], v[8:11], off
	s_nop 1
	v_pk_mul_f32 v[8:9], v[110:111], v[80:81] op_sel_hi:[1,0]
	v_pk_mul_f32 v[10:11], v[104:105], v[80:81] op_sel_hi:[1,0]
	v_pk_fma_f32 v[8:9], v[32:33], v[8:9], v[52:53]
	v_pk_fma_f32 v[10:11], v[34:35], v[10:11], v[54:55]
	v_pk_mul_f32 v[8:9], v[114:115], v[8:9]
	v_pk_mul_f32 v[10:11], v[108:109], v[10:11]
	v_cvt_pk_bf16_f32 v8, v8, v9
	v_cvt_pk_bf16_f32 v9, v10, v11
	v_pk_mul_f32 v[40:41], v[122:123], v[80:81] op_sel_hi:[1,0]
	v_pk_mul_f32 v[42:43], v[116:117], v[80:81] op_sel_hi:[1,0]
	v_pk_fma_f32 v[40:41], v[28:29], v[40:41], v[56:57]
	v_pk_fma_f32 v[42:43], v[30:31], v[42:43], v[58:59]
	v_pk_mul_f32 v[40:41], v[126:127], v[40:41]
	v_pk_mul_f32 v[42:43], v[120:121], v[42:43]
	v_cvt_pk_bf16_f32 v10, v40, v41
	v_cvt_pk_bf16_f32 v11, v42, v43
	s_nop 1
	v_permlane16_swap_b32 v8, v10
	v_permlane16_swap_b32 v9, v11
	global_store_dwordx4 v[0:1], v[8:11], off offset:64
	s_nop 1
	v_pk_mul_f32 v[8:9], v[134:135], v[80:81] op_sel_hi:[1,0]
	v_pk_mul_f32 v[10:11], v[128:129], v[80:81] op_sel_hi:[1,0]
	v_pk_fma_f32 v[8:9], v[24:25], v[8:9], v[72:73]
	v_pk_fma_f32 v[10:11], v[26:27], v[10:11], v[74:75]
	v_pk_mul_f32 v[8:9], v[70:71], v[8:9]
	v_pk_mul_f32 v[10:11], v[132:133], v[10:11]
	v_cvt_pk_bf16_f32 v8, v8, v9
	v_cvt_pk_bf16_f32 v9, v10, v11
	v_pk_mul_f32 v[40:41], v[18:19], v[80:81] op_sel_hi:[1,0]
	v_pk_mul_f32 v[42:43], v[138:139], v[80:81] op_sel_hi:[1,0]
	v_pk_fma_f32 v[40:41], v[20:21], v[40:41], v[76:77]
	v_pk_fma_f32 v[42:43], v[42:43], v[22:23], v[78:79]
	v_pk_mul_f32 v[40:41], v[68:69], v[40:41]
	v_pk_mul_f32 v[42:43], v[142:143], v[42:43]
	v_cvt_pk_bf16_f32 v10, v40, v41
	v_cvt_pk_bf16_f32 v11, v42, v43
	s_nop 1
	v_permlane16_swap_b32 v8, v10
	v_permlane16_swap_b32 v9, v11
	global_store_dwordx4 v[0:1], v[8:11], off offset:128
	s_nop 1
	ds_read_b128 v[8:11], v83 offset:384
	ds_read_b128 v[12:15], v148 offset:384
	s_waitcnt vmcnt(4)
	v_lshlrev_b32_e32 v18, 16, v66
	v_and_b32_e32 v19, 0xffff0000, v66
	v_pk_mul_f32 v[16:17], v[16:17], v[80:81] op_sel_hi:[1,0]
	v_mul_f32_e32 v20, 0xbfb8aa3b, v18
	s_waitcnt lgkmcnt(0)
	v_pk_fma_f32 v[8:9], v[16:17], v[8:9], v[12:13]
	v_mul_f32_e32 v12, 0xbfb8aa3b, v19
	v_exp_f32_e32 v20, v20
	v_exp_f32_e32 v12, v12
	v_pk_mul_f32 v[6:7], v[6:7], v[80:81] op_sel_hi:[1,0]
	v_pk_mul_f32 v[4:5], v[4:5], v[80:81] op_sel_hi:[1,0]
	v_add_f32_e32 v20, 1.0, v20
	v_add_f32_e32 v12, 1.0, v12
	v_rcp_f32_e32 v20, v20
	v_rcp_f32_e32 v21, v12
	v_pk_fma_f32 v[6:7], v[6:7], v[10:11], v[14:15]
	s_waitcnt vmcnt(3)
	v_lshlrev_b32_e32 v14, 16, v64
	v_and_b32_e32 v15, 0xffff0000, v64
	v_pk_mul_f32 v[12:13], v[20:21], v[18:19]
	v_pk_mul_f32 v[2:3], v[2:3], v[80:81] op_sel_hi:[1,0]
	v_pk_mul_f32 v[8:9], v[12:13], v[8:9]
	v_lshlrev_b32_e32 v12, 16, v67
	v_cvt_pk_bf16_f32 v8, v8, v9
	v_mul_f32_e32 v9, 0xbfb8aa3b, v12
	v_exp_f32_e32 v9, v9
	v_and_b32_e32 v13, 0xffff0000, v67
	v_add_f32_e32 v9, 1.0, v9
	v_rcp_f32_e32 v16, v9
	v_mul_f32_e32 v9, 0xbfb8aa3b, v13
	v_exp_f32_e32 v9, v9
	s_nop 0
	v_add_f32_e32 v9, 1.0, v9
	v_rcp_f32_e32 v17, v9
	s_nop 0
	v_pk_mul_f32 v[10:11], v[16:17], v[12:13]
	s_nop 0
	v_pk_mul_f32 v[6:7], v[10:11], v[6:7]
	v_mul_f32_e32 v16, 0xbfb8aa3b, v14
	v_cvt_pk_bf16_f32 v9, v6, v7
	v_mov_b32_e32 v84, v8
	v_mov_b32_e32 v85, v9
	ds_read_b128 v[6:9], v83 offset:448
	ds_read_b128 v[10:13], v148 offset:448
	v_exp_f32_e32 v16, v16
	s_waitcnt lgkmcnt(0)
	v_pk_fma_f32 v[4:5], v[4:5], v[6:7], v[10:11]
	v_mul_f32_e32 v6, 0xbfb8aa3b, v15
	v_exp_f32_e32 v6, v6
	v_add_f32_e32 v16, 1.0, v16
	v_rcp_f32_e32 v16, v16
	v_pk_fma_f32 v[2:3], v[2:3], v[8:9], v[12:13]
	v_add_f32_e32 v6, 1.0, v6
	v_rcp_f32_e32 v17, v6
	s_nop 0
	v_pk_mul_f32 v[6:7], v[16:17], v[14:15]
	s_nop 0
	v_pk_mul_f32 v[4:5], v[6:7], v[4:5]
	v_lshlrev_b32_e32 v6, 16, v65
	v_cvt_pk_bf16_f32 v86, v4, v5
	v_mul_f32_e32 v5, 0xbfb8aa3b, v6
	v_exp_f32_e32 v5, v5
	v_and_b32_e32 v7, 0xffff0000, v65
	v_add_f32_e32 v5, 1.0, v5
	v_rcp_f32_e32 v10, v5
	v_mul_f32_e32 v5, 0xbfb8aa3b, v7
	v_exp_f32_e32 v5, v5
	s_nop 0
	v_add_f32_e32 v5, 1.0, v5
	v_rcp_f32_e32 v11, v5
	s_nop 0
	v_pk_mul_f32 v[6:7], v[10:11], v[6:7]
	s_nop 0
	v_pk_mul_f32 v[2:3], v[6:7], v[2:3]
	s_nop 0
	v_cvt_pk_bf16_f32 v87, v2, v3
	s_nop 1
	v_permlane16_swap_b32 v84, v86
	v_permlane16_swap_b32 v85, v87
	global_store_dwordx4 v[0:1], v[84:87], off offset:192
	s_cbranch_scc1 .LBB0_189
